# P4 pooling d-pass (window 16): prefix-row loads issued together, conversion deferred behind the main loads' wait
# baseline (speedup 1.0000x reference)
; __device__ __forceinline__ float bf_lo(unsigned w) { return __uint_as_float(w << 16); }
; __device__ __forceinline__ float bf_hi(unsigned w) { return __uint_as_float(w & 0xffff0000u); }
; template <int GI> __device__ __forceinline__ void p4_dpass(const bf16_t* XB, const float* cache, bf16_t* Dm, int strip, int lane) {
;     ...
; #pragma unroll
;     for (int i = 0; i < NR; ++i) {
;         if (i >= W - 1 || pos0 != 0) { const u32x2 w = *(const u32x2*)(XB + (size_t)(tok0 - (W - 1) + i) * 1024 + c); rows[i] = (f32x4){bf_lo(w.x), bf_hi(w.x), bf_lo(w.y), bf_hi(w.y)}; }
;         else if (samp) rows[i] = *(const f32x4*)(cache + ((size_t)b * 15 + 15 - (W - 1) + i) * 1024 + c);
;         else rows[i] = (f32x4){0.f, 0.f, 0.f, 0.f};
;     }
.LBB0_684:
	s_ashr_i32 s43, s42, 31
	s_lshl_b64 s[34:35], s[42:43], 11
	v_lshl_add_u64 v[0:1], v[68:69], 0, s[34:35]
	v_add_co_u32_e32 v0, vcc, 0xffff9000, v0
	s_nop 1
	v_addc_co_u32_e32 v1, vcc, -1, v1, vcc
	global_load_dwordx2 v[158:159], v[0:1], off offset:-2048
	v_lshlrev_b32_e32 v60, 2, v62
	s_waitcnt lgkmcnt(0)
	v_lshl_add_u64 v[84:85], s[44:45], 0, v[60:61]
	s_cbranch_execz .LBB0_688
	s_branch .LBB0_690

; __device__ __forceinline__ float bf_lo(unsigned w) { return __uint_as_float(w << 16); }
; __device__ __forceinline__ float bf_hi(unsigned w) { return __uint_as_float(w & 0xffff0000u); }
; template <int GI> __device__ __forceinline__ void p4_dpass(const bf16_t* XB, const float* cache, bf16_t* Dm, int strip, int lane) {
;     ...
; #pragma unroll
;     for (int i = 0; i < NR; ++i) {
;         if (i >= W - 1 || pos0 != 0) { const u32x2 w = *(const u32x2*)(XB + (size_t)(tok0 - (W - 1) + i) * 1024 + c); rows[i] = (f32x4){bf_lo(w.x), bf_hi(w.x), bf_lo(w.y), bf_hi(w.y)}; }
;         else if (samp) rows[i] = *(const f32x4*)(cache + ((size_t)b * 15 + 15 - (W - 1) + i) * 1024 + c);
;         else rows[i] = (f32x4){0.f, 0.f, 0.f, 0.f};
;     }
.LBB0_690:
	s_and_b64 vcc, exec, s[48:49]
	s_cbranch_vccz .LBB0_692
	s_ashr_i32 s43, s42, 31
	s_lshl_b64 s[34:35], s[42:43], 11
	v_lshl_add_u64 v[0:1], v[68:69], 0, s[34:35]
	v_add_co_u32_e32 v0, vcc, 0xffff9000, v0
	s_nop 1
	v_addc_co_u32_e32 v1, vcc, -1, v1, vcc
	global_load_dwordx2 v[160:161], v[0:1], off
	s_cbranch_execz .LBB0_693
	s_branch .LBB0_695

; __device__ __forceinline__ float bf_lo(unsigned w) { return __uint_as_float(w << 16); }
; __device__ __forceinline__ float bf_hi(unsigned w) { return __uint_as_float(w & 0xffff0000u); }
; template <int GI> __device__ __forceinline__ void p4_dpass(const bf16_t* XB, const float* cache, bf16_t* Dm, int strip, int lane) {
;     ...
; #pragma unroll
;     for (int i = 0; i < NR; ++i) {
;         if (i >= W - 1 || pos0 != 0) { const u32x2 w = *(const u32x2*)(XB + (size_t)(tok0 - (W - 1) + i) * 1024 + c); rows[i] = (f32x4){bf_lo(w.x), bf_hi(w.x), bf_lo(w.y), bf_hi(w.y)}; }
;         else if (samp) rows[i] = *(const f32x4*)(cache + ((size_t)b * 15 + 15 - (W - 1) + i) * 1024 + c);
;         else rows[i] = (f32x4){0.f, 0.f, 0.f, 0.f};
;     }
.LBB0_695:
	s_and_b64 vcc, exec, s[48:49]
	s_cbranch_vccz .LBB0_697
	s_ashr_i32 s43, s42, 31
	s_lshl_b64 s[34:35], s[42:43], 11
	v_lshl_add_u64 v[4:5], v[68:69], 0, s[34:35]
	v_add_co_u32_e32 v4, vcc, 0xffffa000, v4
	s_nop 1
	v_addc_co_u32_e32 v5, vcc, -1, v5, vcc
	global_load_dwordx2 v[162:163], v[4:5], off offset:-2048
	s_cbranch_execz .LBB0_698
	s_branch .LBB0_700

; __device__ __forceinline__ float bf_lo(unsigned w) { return __uint_as_float(w << 16); }
; __device__ __forceinline__ float bf_hi(unsigned w) { return __uint_as_float(w & 0xffff0000u); }
; template <int GI> __device__ __forceinline__ void p4_dpass(const bf16_t* XB, const float* cache, bf16_t* Dm, int strip, int lane) {
;     ...
; #pragma unroll
;     for (int i = 0; i < NR; ++i) {
;         if (i >= W - 1 || pos0 != 0) { const u32x2 w = *(const u32x2*)(XB + (size_t)(tok0 - (W - 1) + i) * 1024 + c); rows[i] = (f32x4){bf_lo(w.x), bf_hi(w.x), bf_lo(w.y), bf_hi(w.y)}; }
;         else if (samp) rows[i] = *(const f32x4*)(cache + ((size_t)b * 15 + 15 - (W - 1) + i) * 1024 + c);
;         else rows[i] = (f32x4){0.f, 0.f, 0.f, 0.f};
;     }
.LBB0_700:
	s_and_b64 vcc, exec, s[48:49]
	s_cbranch_vccz .LBB0_702
	s_ashr_i32 s43, s42, 31
	s_lshl_b64 s[34:35], s[42:43], 11
	v_lshl_add_u64 v[8:9], v[68:69], 0, s[34:35]
	v_add_co_u32_e32 v8, vcc, 0xffffa000, v8
	s_nop 1
	v_addc_co_u32_e32 v9, vcc, -1, v9, vcc
	global_load_dwordx2 v[164:165], v[8:9], off
	s_cbranch_execz .LBB0_703
	s_branch .LBB0_705

; __device__ __forceinline__ float bf_lo(unsigned w) { return __uint_as_float(w << 16); }
; __device__ __forceinline__ float bf_hi(unsigned w) { return __uint_as_float(w & 0xffff0000u); }
; template <int GI> __device__ __forceinline__ void p4_dpass(const bf16_t* XB, const float* cache, bf16_t* Dm, int strip, int lane) {
;     ...
; #pragma unroll
;     for (int i = 0; i < NR; ++i) {
;         if (i >= W - 1 || pos0 != 0) { const u32x2 w = *(const u32x2*)(XB + (size_t)(tok0 - (W - 1) + i) * 1024 + c); rows[i] = (f32x4){bf_lo(w.x), bf_hi(w.x), bf_lo(w.y), bf_hi(w.y)}; }
;         else if (samp) rows[i] = *(const f32x4*)(cache + ((size_t)b * 15 + 15 - (W - 1) + i) * 1024 + c);
;         else rows[i] = (f32x4){0.f, 0.f, 0.f, 0.f};
;     }
.LBB0_705:
	s_and_b64 vcc, exec, s[48:49]
	s_cbranch_vccz .LBB0_707
	s_ashr_i32 s43, s42, 31
	s_lshl_b64 s[34:35], s[42:43], 11
	v_lshl_add_u64 v[16:17], v[68:69], 0, s[34:35]
	v_add_co_u32_e32 v16, vcc, 0xffffb000, v16
	s_nop 1
	v_addc_co_u32_e32 v17, vcc, -1, v17, vcc
	global_load_dwordx2 v[166:167], v[16:17], off offset:-2048
	s_cbranch_execz .LBB0_708
	s_branch .LBB0_710

; __device__ __forceinline__ float bf_lo(unsigned w) { return __uint_as_float(w << 16); }
; __device__ __forceinline__ float bf_hi(unsigned w) { return __uint_as_float(w & 0xffff0000u); }
; template <int GI> __device__ __forceinline__ void p4_dpass(const bf16_t* XB, const float* cache, bf16_t* Dm, int strip, int lane) {
;     ...
; #pragma unroll
;     for (int i = 0; i < NR; ++i) {
;         if (i >= W - 1 || pos0 != 0) { const u32x2 w = *(const u32x2*)(XB + (size_t)(tok0 - (W - 1) + i) * 1024 + c); rows[i] = (f32x4){bf_lo(w.x), bf_hi(w.x), bf_lo(w.y), bf_hi(w.y)}; }
;         else if (samp) rows[i] = *(const f32x4*)(cache + ((size_t)b * 15 + 15 - (W - 1) + i) * 1024 + c);
;         else rows[i] = (f32x4){0.f, 0.f, 0.f, 0.f};
;     }
.LBB0_710:
	s_and_b64 vcc, exec, s[48:49]
	s_cbranch_vccz .LBB0_712
	s_ashr_i32 s43, s42, 31
	s_lshl_b64 s[34:35], s[42:43], 11
	v_lshl_add_u64 v[20:21], v[68:69], 0, s[34:35]
	v_add_co_u32_e32 v20, vcc, 0xffffb000, v20
	s_nop 1
	v_addc_co_u32_e32 v21, vcc, -1, v21, vcc
	global_load_dwordx2 v[168:169], v[20:21], off
	s_cbranch_execz .LBB0_713
	s_branch .LBB0_715

; __device__ __forceinline__ float bf_lo(unsigned w) { return __uint_as_float(w << 16); }
; __device__ __forceinline__ float bf_hi(unsigned w) { return __uint_as_float(w & 0xffff0000u); }
; template <int GI> __device__ __forceinline__ void p4_dpass(const bf16_t* XB, const float* cache, bf16_t* Dm, int strip, int lane) {
;     ...
; #pragma unroll
;     for (int i = 0; i < NR; ++i) {
;         if (i >= W - 1 || pos0 != 0) { const u32x2 w = *(const u32x2*)(XB + (size_t)(tok0 - (W - 1) + i) * 1024 + c); rows[i] = (f32x4){bf_lo(w.x), bf_hi(w.x), bf_lo(w.y), bf_hi(w.y)}; }
;         else if (samp) rows[i] = *(const f32x4*)(cache + ((size_t)b * 15 + 15 - (W - 1) + i) * 1024 + c);
;         else rows[i] = (f32x4){0.f, 0.f, 0.f, 0.f};
;     }
.LBB0_715:
	s_and_b64 vcc, exec, s[48:49]
	s_cbranch_vccz .LBB0_717
	s_ashr_i32 s43, s42, 31
	s_lshl_b64 s[34:35], s[42:43], 11
	v_lshl_add_u64 v[24:25], v[68:69], 0, s[34:35]
	v_add_co_u32_e32 v24, vcc, 0xffffc000, v24
	s_nop 1
	v_addc_co_u32_e32 v25, vcc, -1, v25, vcc
	global_load_dwordx2 v[170:171], v[24:25], off offset:-2048
	s_cbranch_execz .LBB0_718
	s_branch .LBB0_720

; __device__ __forceinline__ float bf_lo(unsigned w) { return __uint_as_float(w << 16); }
; __device__ __forceinline__ float bf_hi(unsigned w) { return __uint_as_float(w & 0xffff0000u); }
; template <int GI> __device__ __forceinline__ void p4_dpass(const bf16_t* XB, const float* cache, bf16_t* Dm, int strip, int lane) {
;     ...
; #pragma unroll
;     for (int i = 0; i < NR; ++i) {
;         if (i >= W - 1 || pos0 != 0) { const u32x2 w = *(const u32x2*)(XB + (size_t)(tok0 - (W - 1) + i) * 1024 + c); rows[i] = (f32x4){bf_lo(w.x), bf_hi(w.x), bf_lo(w.y), bf_hi(w.y)}; }
;         else if (samp) rows[i] = *(const f32x4*)(cache + ((size_t)b * 15 + 15 - (W - 1) + i) * 1024 + c);
;         else rows[i] = (f32x4){0.f, 0.f, 0.f, 0.f};
;     }
.LBB0_720:
	s_and_b64 vcc, exec, s[48:49]
	s_cbranch_vccz .LBB0_722
	s_ashr_i32 s43, s42, 31
	s_lshl_b64 s[34:35], s[42:43], 11
	v_lshl_add_u64 v[28:29], v[68:69], 0, s[34:35]
	v_add_co_u32_e32 v28, vcc, 0xffffc000, v28
	s_nop 1
	v_addc_co_u32_e32 v29, vcc, -1, v29, vcc
	global_load_dwordx2 v[172:173], v[28:29], off
	s_cbranch_execz .LBB0_723
	s_branch .LBB0_725

; __device__ __forceinline__ float bf_lo(unsigned w) { return __uint_as_float(w << 16); }
; __device__ __forceinline__ float bf_hi(unsigned w) { return __uint_as_float(w & 0xffff0000u); }
; template <int GI> __device__ __forceinline__ void p4_dpass(const bf16_t* XB, const float* cache, bf16_t* Dm, int strip, int lane) {
;     ...
; #pragma unroll
;     for (int i = 0; i < NR; ++i) {
;         if (i >= W - 1 || pos0 != 0) { const u32x2 w = *(const u32x2*)(XB + (size_t)(tok0 - (W - 1) + i) * 1024 + c); rows[i] = (f32x4){bf_lo(w.x), bf_hi(w.x), bf_lo(w.y), bf_hi(w.y)}; }
;         else if (samp) rows[i] = *(const f32x4*)(cache + ((size_t)b * 15 + 15 - (W - 1) + i) * 1024 + c);
;         else rows[i] = (f32x4){0.f, 0.f, 0.f, 0.f};
;     }
.LBB0_725:
	s_and_b64 vcc, exec, s[48:49]
	s_cbranch_vccz .LBB0_727
	s_ashr_i32 s43, s42, 31
	s_lshl_b64 s[34:35], s[42:43], 11
	v_lshl_add_u64 v[32:33], v[68:69], 0, s[34:35]
	v_add_co_u32_e32 v32, vcc, 0xffffd000, v32
	s_nop 1
	v_addc_co_u32_e32 v33, vcc, -1, v33, vcc
	global_load_dwordx2 v[174:175], v[32:33], off offset:-2048
	s_cbranch_execz .LBB0_728
	s_branch .LBB0_730

; __device__ __forceinline__ float bf_lo(unsigned w) { return __uint_as_float(w << 16); }
; __device__ __forceinline__ float bf_hi(unsigned w) { return __uint_as_float(w & 0xffff0000u); }
; template <int GI> __device__ __forceinline__ void p4_dpass(const bf16_t* XB, const float* cache, bf16_t* Dm, int strip, int lane) {
;     ...
; #pragma unroll
;     for (int i = 0; i < NR; ++i) {
;         if (i >= W - 1 || pos0 != 0) { const u32x2 w = *(const u32x2*)(XB + (size_t)(tok0 - (W - 1) + i) * 1024 + c); rows[i] = (f32x4){bf_lo(w.x), bf_hi(w.x), bf_lo(w.y), bf_hi(w.y)}; }
;         else if (samp) rows[i] = *(const f32x4*)(cache + ((size_t)b * 15 + 15 - (W - 1) + i) * 1024 + c);
;         else rows[i] = (f32x4){0.f, 0.f, 0.f, 0.f};
;     }
.LBB0_730:
	s_and_b64 vcc, exec, s[48:49]
	s_cbranch_vccz .LBB0_732
	s_ashr_i32 s43, s42, 31
	s_lshl_b64 s[34:35], s[42:43], 11
	v_lshl_add_u64 v[36:37], v[68:69], 0, s[34:35]
	v_add_co_u32_e32 v36, vcc, 0xffffd000, v36
	s_nop 1
	v_addc_co_u32_e32 v37, vcc, -1, v37, vcc
	global_load_dwordx2 v[176:177], v[36:37], off
	s_cbranch_execz .LBB0_733
	s_branch .LBB0_735

; __device__ __forceinline__ float bf_lo(unsigned w) { return __uint_as_float(w << 16); }
; __device__ __forceinline__ float bf_hi(unsigned w) { return __uint_as_float(w & 0xffff0000u); }
; template <int GI> __device__ __forceinline__ void p4_dpass(const bf16_t* XB, const float* cache, bf16_t* Dm, int strip, int lane) {
;     ...
; #pragma unroll
;     for (int i = 0; i < NR; ++i) {
;         if (i >= W - 1 || pos0 != 0) { const u32x2 w = *(const u32x2*)(XB + (size_t)(tok0 - (W - 1) + i) * 1024 + c); rows[i] = (f32x4){bf_lo(w.x), bf_hi(w.x), bf_lo(w.y), bf_hi(w.y)}; }
;         else if (samp) rows[i] = *(const f32x4*)(cache + ((size_t)b * 15 + 15 - (W - 1) + i) * 1024 + c);
;         else rows[i] = (f32x4){0.f, 0.f, 0.f, 0.f};
;     }
.LBB0_735:
	s_and_b64 vcc, exec, s[48:49]
	s_cbranch_vccz .LBB0_737
	s_ashr_i32 s43, s42, 31
	s_lshl_b64 s[34:35], s[42:43], 11
	v_lshl_add_u64 v[40:41], v[68:69], 0, s[34:35]
	v_add_co_u32_e32 v40, vcc, 0xffffe000, v40
	s_nop 1
	v_addc_co_u32_e32 v41, vcc, -1, v41, vcc
	global_load_dwordx2 v[178:179], v[40:41], off offset:-2048
	s_cbranch_execz .LBB0_738
	s_branch .LBB0_740

; __device__ __forceinline__ float bf_lo(unsigned w) { return __uint_as_float(w << 16); }
; __device__ __forceinline__ float bf_hi(unsigned w) { return __uint_as_float(w & 0xffff0000u); }
; template <int GI> __device__ __forceinline__ void p4_dpass(const bf16_t* XB, const float* cache, bf16_t* Dm, int strip, int lane) {
;     ...
; #pragma unroll
;     for (int i = 0; i < NR; ++i) {
;         if (i >= W - 1 || pos0 != 0) { const u32x2 w = *(const u32x2*)(XB + (size_t)(tok0 - (W - 1) + i) * 1024 + c); rows[i] = (f32x4){bf_lo(w.x), bf_hi(w.x), bf_lo(w.y), bf_hi(w.y)}; }
;         else if (samp) rows[i] = *(const f32x4*)(cache + ((size_t)b * 15 + 15 - (W - 1) + i) * 1024 + c);
;         else rows[i] = (f32x4){0.f, 0.f, 0.f, 0.f};
;     }
.LBB0_740:
	s_and_b64 vcc, exec, s[48:49]
	s_cbranch_vccz .LBB0_742
	s_ashr_i32 s43, s42, 31
	s_lshl_b64 s[34:35], s[42:43], 11
	v_lshl_add_u64 v[44:45], v[68:69], 0, s[34:35]
	v_add_co_u32_e32 v44, vcc, 0xffffe000, v44
	s_nop 1
	v_addc_co_u32_e32 v45, vcc, -1, v45, vcc
	global_load_dwordx2 v[180:181], v[44:45], off
	s_cbranch_execz .LBB0_743
	s_branch .LBB0_745

; __device__ __forceinline__ float bf_lo(unsigned w) { return __uint_as_float(w << 16); }
; __device__ __forceinline__ float bf_hi(unsigned w) { return __uint_as_float(w & 0xffff0000u); }
; template <int GI> __device__ __forceinline__ void p4_dpass(const bf16_t* XB, const float* cache, bf16_t* Dm, int strip, int lane) {
;     ...
; #pragma unroll
;     for (int i = 0; i < NR; ++i) {
;         if (i >= W - 1 || pos0 != 0) { const u32x2 w = *(const u32x2*)(XB + (size_t)(tok0 - (W - 1) + i) * 1024 + c); rows[i] = (f32x4){bf_lo(w.x), bf_hi(w.x), bf_lo(w.y), bf_hi(w.y)}; }
;         else if (samp) rows[i] = *(const f32x4*)(cache + ((size_t)b * 15 + 15 - (W - 1) + i) * 1024 + c);
;         else rows[i] = (f32x4){0.f, 0.f, 0.f, 0.f};
;     }
.LBB0_745:
	s_and_b64 vcc, exec, s[48:49]
	s_cbranch_vccz .LBB0_747
	s_ashr_i32 s43, s42, 31
	s_lshl_b64 s[34:35], s[42:43], 11
	v_lshl_add_u64 v[48:49], v[68:69], 0, s[34:35]
	v_add_co_u32_e32 v48, vcc, 0xfffff000, v48
	s_nop 1
	v_addc_co_u32_e32 v49, vcc, -1, v49, vcc
	global_load_dwordx2 v[182:183], v[48:49], off offset:-2048
	s_cbranch_execz .LBB0_748
	s_branch .LBB0_750

; __device__ __forceinline__ float bf_lo(unsigned w) { return __uint_as_float(w << 16); }
; __device__ __forceinline__ float bf_hi(unsigned w) { return __uint_as_float(w & 0xffff0000u); }
; template <int GI> __device__ __forceinline__ void p4_dpass(const bf16_t* XB, const float* cache, bf16_t* Dm, int strip, int lane) {
;     ...
; #pragma unroll
;     for (int i = 0; i < NR; ++i) {
;         if (i >= W - 1 || pos0 != 0) { const u32x2 w = *(const u32x2*)(XB + (size_t)(tok0 - (W - 1) + i) * 1024 + c); rows[i] = (f32x4){bf_lo(w.x), bf_hi(w.x), bf_lo(w.y), bf_hi(w.y)}; }
;         else if (samp) rows[i] = *(const f32x4*)(cache + ((size_t)b * 15 + 15 - (W - 1) + i) * 1024 + c);
;         else rows[i] = (f32x4){0.f, 0.f, 0.f, 0.f};
;     }
.LBB0_750:
	s_and_b64 vcc, exec, s[48:49]
	s_cbranch_vccz .LBB0_752
	s_ashr_i32 s43, s42, 31
	s_lshl_b64 s[34:35], s[42:43], 11
	v_lshl_add_u64 v[52:53], v[68:69], 0, s[34:35]
	global_load_dwordx2 v[184:185], v[52:53], off offset:-4096
	s_cbranch_execz .LBB0_753
	s_branch .LBB0_755

; __device__ __forceinline__ float bf_lo(unsigned w) { return __uint_as_float(w << 16); }
; __device__ __forceinline__ float bf_hi(unsigned w) { return __uint_as_float(w & 0xffff0000u); }
; template <int GI> __device__ __forceinline__ void p4_dpass(const bf16_t* XB, const float* cache, bf16_t* Dm, int strip, int lane) {
;     ...
; #pragma unroll
;     for (int i = 0; i < NR; ++i) {
;         if (i >= W - 1 || pos0 != 0) { const u32x2 w = *(const u32x2*)(XB + (size_t)(tok0 - (W - 1) + i) * 1024 + c); rows[i] = (f32x4){bf_lo(w.x), bf_hi(w.x), bf_lo(w.y), bf_hi(w.y)}; }
;         else if (samp) rows[i] = *(const f32x4*)(cache + ((size_t)b * 15 + 15 - (W - 1) + i) * 1024 + c);
;         else rows[i] = (f32x4){0.f, 0.f, 0.f, 0.f};
;     }
.LBB0_755:
	s_and_b64 vcc, exec, s[48:49]
	s_cbranch_vccz .LBB0_757
	s_ashr_i32 s43, s42, 31
	s_lshl_b64 s[34:35], s[42:43], 11
	v_lshl_add_u64 v[56:57], v[68:69], 0, s[34:35]
	global_load_dwordx2 v[186:187], v[56:57], off offset:-2048
	s_cbranch_execz .LBB0_758
	s_branch .LBB0_760

; __device__ __forceinline__ float bf_lo(unsigned w) { return __uint_as_float(w << 16); }
; __device__ __forceinline__ float bf_hi(unsigned w) { return __uint_as_float(w & 0xffff0000u); }
; template <int GI> __device__ __forceinline__ void p4_dpass(const bf16_t* XB, const float* cache, bf16_t* Dm, int strip, int lane) {
;     ...
; #pragma unroll
;     for (int i = 0; i < NR; ++i) {
;         if (i >= W - 1 || pos0 != 0) { const u32x2 w = *(const u32x2*)(XB + (size_t)(tok0 - (W - 1) + i) * 1024 + c); rows[i] = (f32x4){bf_lo(w.x), bf_hi(w.x), bf_lo(w.y), bf_hi(w.y)}; }
;         else if (samp) rows[i] = *(const f32x4*)(cache + ((size_t)b * 15 + 15 - (W - 1) + i) * 1024 + c);
;         else rows[i] = (f32x4){0.f, 0.f, 0.f, 0.f};
;     }
.LBB0_760:
	s_mov_b64 s[94:95], s[48:49]
	s_or_b32 s34, s42, 12
	s_ashr_i32 s35, s34, 31
	s_lshl_b64 s[52:53], s[34:35], 11
	s_or_b32 s34, s42, 13
	s_ashr_i32 s35, s34, 31
	s_lshl_b64 s[50:51], s[34:35], 11
	s_or_b32 s34, s42, 14
	s_ashr_i32 s35, s34, 31
	s_lshl_b64 s[48:49], s[34:35], 11
	s_or_b32 s34, s42, 15
	s_ashr_i32 s35, s34, 31
	s_lshl_b64 s[46:47], s[34:35], 11
	s_or_b32 s34, s42, 8
	s_ashr_i32 s35, s34, 31
	s_lshl_b64 s[60:61], s[34:35], 11
	s_or_b32 s34, s42, 9
	s_ashr_i32 s35, s34, 31
	s_lshl_b64 s[58:59], s[34:35], 11
	s_or_b32 s34, s42, 10
	s_ashr_i32 s35, s34, 31
	s_or_b32 s54, s42, 11
	s_lshl_b64 s[56:57], s[34:35], 11
	s_or_b32 s34, s42, 4
	s_or_b32 s62, s42, 6
	s_ashr_i32 s55, s54, 31
	s_ashr_i32 s63, s62, 31
	s_ashr_i32 s35, s34, 31
	s_lshl_b64 s[54:55], s[54:55], 11
	s_lshl_b64 s[64:65], s[62:63], 11
	s_or_b32 s62, s42, 7
	s_lshl_b64 s[68:69], s[34:35], 11
	s_or_b32 s34, s42, 5
	v_lshl_add_u64 v[84:85], v[68:69], 0, s[52:53]
	v_lshl_add_u64 v[86:87], v[68:69], 0, s[50:51]
	v_lshl_add_u64 v[88:89], v[68:69], 0, s[48:49]
	v_lshl_add_u64 v[90:91], v[68:69], 0, s[46:47]
	v_lshl_add_u64 v[92:93], v[68:69], 0, s[54:55]
	s_ashr_i32 s63, s62, 31
	s_ashr_i32 s35, s34, 31
	global_load_dwordx2 v[98:99], v[84:85], off
	global_load_dwordx2 v[94:95], v[86:87], off
	s_nop 0
	global_load_dwordx2 v[86:87], v[90:91], off
	s_nop 0
	global_load_dwordx2 v[90:91], v[88:89], off
	v_lshl_add_u64 v[84:85], v[68:69], 0, s[60:61]
	v_lshl_add_u64 v[88:89], v[68:69], 0, s[58:59]
	global_load_dwordx2 v[102:103], v[92:93], off
	v_lshl_add_u64 v[92:93], v[68:69], 0, s[56:57]
	s_lshl_b64 s[62:63], s[62:63], 11
	s_lshl_b64 s[66:67], s[34:35], 11
	s_or_b32 s34, s42, 2
	s_or_b32 s70, s42, 3
	global_load_dwordx2 v[106:107], v[92:93], off
	global_load_dwordx2 v[114:115], v[84:85], off
	global_load_dwordx2 v[110:111], v[88:89], off
	v_lshl_add_u64 v[84:85], v[68:69], 0, s[64:65]
	v_lshl_add_u64 v[88:89], v[68:69], 0, s[62:63]
	s_ashr_i32 s35, s34, 31
	s_ashr_i32 s71, s70, 31
	global_load_dwordx2 v[122:123], v[84:85], off
	global_load_dwordx2 v[118:119], v[88:89], off
	v_lshl_add_u64 v[84:85], v[68:69], 0, s[68:69]
	v_lshl_add_u64 v[88:89], v[68:69], 0, s[66:67]
	s_lshl_b64 s[70:71], s[70:71], 11
	s_lshl_b64 s[72:73], s[34:35], 11
	s_or_b32 s34, s42, 1
	global_load_dwordx2 v[126:127], v[88:89], off
	global_load_dwordx2 v[130:131], v[84:85], off
	v_lshl_add_u64 v[84:85], v[68:69], 0, s[70:71]
	s_ashr_i32 s35, s34, 31
	global_load_dwordx2 v[134:135], v[84:85], off
	v_lshl_add_u64 v[84:85], v[68:69], 0, s[72:73]
	s_lshl_b64 s[74:75], s[34:35], 11
	s_ashr_i32 s43, s42, 31
	global_load_dwordx2 v[138:139], v[84:85], off
	v_lshl_add_u64 v[84:85], v[68:69], 0, s[74:75]
	s_lshl_b64 s[76:77], s[42:43], 11
	global_load_dwordx2 v[142:143], v[84:85], off
	v_lshl_add_u64 v[84:85], v[68:69], 0, s[76:77]
	global_load_dwordx2 v[146:147], v[84:85], off
	s_min_u32 s22, s27, 15
	s_add_i32 s22, s22, 1
	s_waitcnt vmcnt(16)
	s_and_b64 vcc, exec, s[94:95]
	s_cbranch_vccz .Lpool3_noconv
	v_lshlrev_b32_e32 v12, 16, v158
	v_and_b32_e32 v13, 0xffff0000, v158
	v_lshlrev_b32_e32 v14, 16, v159
	v_and_b32_e32 v15, 0xffff0000, v159
	v_lshlrev_b32_e32 v0, 16, v160
	v_and_b32_e32 v1, 0xffff0000, v160
	v_lshlrev_b32_e32 v2, 16, v161
	v_and_b32_e32 v3, 0xffff0000, v161
	v_lshlrev_b32_e32 v4, 16, v162
	v_and_b32_e32 v5, 0xffff0000, v162
	v_lshlrev_b32_e32 v6, 16, v163
	v_and_b32_e32 v7, 0xffff0000, v163
	v_lshlrev_b32_e32 v8, 16, v164
	v_and_b32_e32 v9, 0xffff0000, v164
	v_lshlrev_b32_e32 v10, 16, v165
	v_and_b32_e32 v11, 0xffff0000, v165
	v_lshlrev_b32_e32 v16, 16, v166
	v_and_b32_e32 v17, 0xffff0000, v166
	v_lshlrev_b32_e32 v18, 16, v167
	v_and_b32_e32 v19, 0xffff0000, v167
	v_lshlrev_b32_e32 v20, 16, v168
	v_and_b32_e32 v21, 0xffff0000, v168
	v_lshlrev_b32_e32 v22, 16, v169
	v_and_b32_e32 v23, 0xffff0000, v169
	v_lshlrev_b32_e32 v24, 16, v170
	v_and_b32_e32 v25, 0xffff0000, v170
	v_lshlrev_b32_e32 v26, 16, v171
	v_and_b32_e32 v27, 0xffff0000, v171
	v_lshlrev_b32_e32 v28, 16, v172
	v_and_b32_e32 v29, 0xffff0000, v172
	v_lshlrev_b32_e32 v30, 16, v173
	v_and_b32_e32 v31, 0xffff0000, v173
	v_lshlrev_b32_e32 v32, 16, v174
	v_and_b32_e32 v33, 0xffff0000, v174
	v_lshlrev_b32_e32 v34, 16, v175
	v_and_b32_e32 v35, 0xffff0000, v175
	v_lshlrev_b32_e32 v36, 16, v176
	v_and_b32_e32 v37, 0xffff0000, v176
	v_lshlrev_b32_e32 v38, 16, v177
	v_and_b32_e32 v39, 0xffff0000, v177
	v_lshlrev_b32_e32 v40, 16, v178
	v_and_b32_e32 v41, 0xffff0000, v178
	v_lshlrev_b32_e32 v42, 16, v179
	v_and_b32_e32 v43, 0xffff0000, v179
	v_lshlrev_b32_e32 v44, 16, v180
	v_and_b32_e32 v45, 0xffff0000, v180
	v_lshlrev_b32_e32 v46, 16, v181
	v_and_b32_e32 v47, 0xffff0000, v181
	v_lshlrev_b32_e32 v48, 16, v182
	v_and_b32_e32 v49, 0xffff0000, v182
	v_lshlrev_b32_e32 v50, 16, v183
	v_and_b32_e32 v51, 0xffff0000, v183
	v_lshlrev_b32_e32 v52, 16, v184
	v_and_b32_e32 v53, 0xffff0000, v184
	v_lshlrev_b32_e32 v54, 16, v185
	v_and_b32_e32 v55, 0xffff0000, v185
	v_lshlrev_b32_e32 v56, 16, v186
	v_and_b32_e32 v57, 0xffff0000, v186
	v_lshlrev_b32_e32 v58, 16, v187
	v_and_b32_e32 v59, 0xffff0000, v187
; __device__ __forceinline__ unsigned pk2(float lo, float hi) { unsigned r; asm volatile("v_cvt_pk_bf16_f32 %0, %1, %2" : "=v"(r) : "v"(lo), "v"(hi)); return r; }
; template <int GI> __device__ __forceinline__ void p4_dpass(const bf16_t* XB, const float* cache, bf16_t* Dm, int strip, int lane) {
;     ...
; #pragma unroll
;     for (int t = 0; t < 16; ++t) {
;         f32x4 s = rows[t];
; #pragma unroll
;         for (int j = 1; j < W; ++j) s += rows[t + j];
;         const int cnt = samp ? W : (W < pos0 + t + 1 ? W : pos0 + t + 1);
;         const f32x4 d = s * (1.0f / (float)cnt) - rows[t + W - 1];
;         u32x2 wv; wv.x = pk2(d[0], d[1]); wv.y = pk2(d[2], d[3]);
;         *(u32x2*)(Dm + (size_t)(tok0 + t) * 1024 + c) = wv;
;     }
.Lpool3_noconv:
	v_pk_add_f32 v[14:15], v[14:15], v[2:3]
	v_cvt_f32_ubyte0_e32 v60, s22
	v_pk_add_f32 v[12:13], v[12:13], v[0:1]
	v_pk_add_f32 v[14:15], v[14:15], v[6:7]
	v_div_scale_f32 v152, s[34:35], v60, v60, 1.0
	v_pk_add_f32 v[12:13], v[12:13], v[4:5]
	v_pk_add_f32 v[14:15], v[14:15], v[10:11]
	v_rcp_f32_e32 v153, v152
	v_pk_add_f32 v[12:13], v[12:13], v[8:9]
	v_pk_add_f32 v[14:15], v[14:15], v[18:19]
	v_pk_add_f32 v[12:13], v[12:13], v[16:17]
	v_pk_add_f32 v[14:15], v[14:15], v[22:23]
	v_pk_add_f32 v[12:13], v[12:13], v[20:21]
	v_pk_add_f32 v[14:15], v[14:15], v[26:27]
	v_pk_add_f32 v[12:13], v[12:13], v[24:25]
	v_pk_add_f32 v[14:15], v[14:15], v[30:31]
	v_fma_f32 v154, -v152, v153, 1.0
	v_pk_add_f32 v[12:13], v[12:13], v[28:29]
	v_pk_add_f32 v[14:15], v[14:15], v[34:35]
	v_fmac_f32_e32 v153, v154, v153
	v_div_scale_f32 v154, vcc, 1.0, v60, 1.0
	v_pk_add_f32 v[12:13], v[12:13], v[32:33]
	v_pk_add_f32 v[14:15], v[14:15], v[38:39]
	v_mul_f32_e32 v155, v154, v153
	v_pk_add_f32 v[12:13], v[12:13], v[36:37]
	v_pk_add_f32 v[14:15], v[14:15], v[42:43]
	v_fma_f32 v156, -v152, v155, v154
	v_pk_add_f32 v[12:13], v[12:13], v[40:41]
	v_pk_add_f32 v[14:15], v[14:15], v[46:47]
	v_fmac_f32_e32 v155, v156, v153
	v_pk_add_f32 v[12:13], v[12:13], v[44:45]
	v_pk_add_f32 v[14:15], v[14:15], v[50:51]
	v_fma_f32 v152, -v152, v155, v154
	v_pk_add_f32 v[12:13], v[12:13], v[48:49]
	v_pk_add_f32 v[14:15], v[14:15], v[54:55]
	v_div_fmas_f32 v152, v152, v153, v155
	v_pk_add_f32 v[12:13], v[12:13], v[52:53]
	v_pk_add_f32 v[14:15], v[14:15], v[58:59]
	v_div_fixup_f32 v60, v152, v60, 1.0
	v_pk_add_f32 v[12:13], v[12:13], v[56:57]
	v_cndmask_b32_e64 v60, v60, v149, s[8:9]
	s_or_b32 s22, s27, 1
	s_min_u32 s22, s22, 15
	s_add_i32 s22, s22, 1
	v_pk_add_f32 v[2:3], v[2:3], v[6:7]
	v_pk_add_f32 v[0:1], v[0:1], v[4:5]
	v_pk_add_f32 v[2:3], v[2:3], v[10:11]
	v_pk_add_f32 v[0:1], v[0:1], v[8:9]
	v_pk_add_f32 v[2:3], v[2:3], v[18:19]
	v_pk_add_f32 v[0:1], v[0:1], v[16:17]
	v_pk_add_f32 v[2:3], v[2:3], v[22:23]
	v_pk_add_f32 v[0:1], v[0:1], v[20:21]
	v_pk_add_f32 v[2:3], v[2:3], v[26:27]
	v_pk_add_f32 v[0:1], v[0:1], v[24:25]
	v_pk_add_f32 v[2:3], v[2:3], v[30:31]
	v_pk_add_f32 v[0:1], v[0:1], v[28:29]
	v_pk_add_f32 v[2:3], v[2:3], v[34:35]
	v_pk_add_f32 v[0:1], v[0:1], v[32:33]
	v_pk_add_f32 v[2:3], v[2:3], v[38:39]
	v_pk_add_f32 v[0:1], v[0:1], v[36:37]
	v_pk_add_f32 v[2:3], v[2:3], v[42:43]
	v_pk_add_f32 v[0:1], v[0:1], v[40:41]
	v_pk_add_f32 v[2:3], v[2:3], v[46:47]
	v_pk_add_f32 v[0:1], v[0:1], v[44:45]
	v_pk_add_f32 v[2:3], v[2:3], v[50:51]
	v_pk_add_f32 v[0:1], v[0:1], v[48:49]
	v_pk_add_f32 v[2:3], v[2:3], v[54:55]
	v_pk_add_f32 v[0:1], v[0:1], v[52:53]
	v_pk_add_f32 v[2:3], v[2:3], v[58:59]
	v_pk_add_f32 v[0:1], v[0:1], v[56:57]
	s_waitcnt vmcnt(2)
	v_lshlrev_b32_e32 v136, 16, v138
	v_and_b32_e32 v137, 0xffff0000, v138
	v_lshlrev_b32_e32 v138, 16, v139
	s_waitcnt vmcnt(1)
	v_lshlrev_b32_e32 v140, 16, v142
	v_and_b32_e32 v141, 0xffff0000, v142
	s_waitcnt vmcnt(0)
	v_lshlrev_b32_e32 v144, 16, v146
	v_and_b32_e32 v145, 0xffff0000, v146
	v_lshlrev_b32_e32 v146, 16, v147
	v_and_b32_e32 v147, 0xffff0000, v147
	v_pk_add_f32 v[14:15], v[14:15], v[146:147]
	v_xor_b32_e32 v153, 0x80000000, v147
	v_xor_b32_e32 v152, 0x80000000, v146
	v_pk_add_f32 v[12:13], v[12:13], v[144:145]
	v_pk_fma_f32 v[14:15], v[60:61], v[14:15], v[152:153] op_sel_hi:[0,1,1]
	v_xor_b32_e32 v153, 0x80000000, v145
	v_xor_b32_e32 v152, 0x80000000, v144
	v_pk_fma_f32 v[12:13], v[60:61], v[12:13], v[152:153] op_sel_hi:[0,1,1]
	v_cvt_pk_bf16_f32 v12, v12, v13
	v_cvt_pk_bf16_f32 v13, v14, v15
	v_lshl_add_u64 v[14:15], v[70:71], 0, s[76:77]
	global_store_dwordx2 v[14:15], v[12:13], off
	v_cvt_f32_ubyte0_e32 v12, s22
	v_div_scale_f32 v13, s[34:35], v12, v12, 1.0
	v_rcp_f32_e32 v14, v13
	v_lshlrev_b32_e32 v142, 16, v143
	v_and_b32_e32 v143, 0xffff0000, v143
	v_pk_add_f32 v[2:3], v[2:3], v[146:147]
	v_fma_f32 v15, -v13, v14, 1.0
	v_fmac_f32_e32 v14, v15, v14
	v_div_scale_f32 v15, vcc, 1.0, v12, 1.0
	v_mul_f32_e32 v60, v15, v14
	v_fma_f32 v152, -v13, v60, v15
	v_fmac_f32_e32 v60, v152, v14
	v_fma_f32 v13, -v13, v60, v15
	v_div_fmas_f32 v13, v13, v14, v60
	v_div_fixup_f32 v12, v13, v12, 1.0
	v_pk_add_f32 v[0:1], v[0:1], v[144:145]
	v_pk_add_f32 v[2:3], v[2:3], v[142:143]
	v_cndmask_b32_e64 v12, v12, v149, s[8:9]
	v_xor_b32_e32 v15, 0x80000000, v143
	v_xor_b32_e32 v14, 0x80000000, v142
	v_pk_add_f32 v[0:1], v[0:1], v[140:141]
	v_pk_fma_f32 v[2:3], v[12:13], v[2:3], v[14:15] op_sel_hi:[0,1,1]
	v_xor_b32_e32 v15, 0x80000000, v141
	v_xor_b32_e32 v14, 0x80000000, v140
	s_or_b32 s22, s27, 2
	v_pk_fma_f32 v[0:1], v[12:13], v[0:1], v[14:15] op_sel_hi:[0,1,1]
	s_min_u32 s22, s22, 15
	v_cvt_pk_bf16_f32 v0, v0, v1
	v_cvt_pk_bf16_f32 v1, v2, v3
	v_lshl_add_u64 v[2:3], v[70:71], 0, s[74:75]
	s_add_i32 s22, s22, 1
	global_store_dwordx2 v[2:3], v[0:1], off
	v_pk_add_f32 v[0:1], v[4:5], v[8:9]
	v_pk_add_f32 v[2:3], v[6:7], v[10:11]
	v_cvt_f32_ubyte0_e32 v4, s22
	v_pk_add_f32 v[2:3], v[2:3], v[18:19]
	v_div_scale_f32 v5, s[34:35], v4, v4, 1.0
	v_pk_add_f32 v[0:1], v[0:1], v[16:17]
	v_pk_add_f32 v[2:3], v[2:3], v[22:23]
	v_rcp_f32_e32 v6, v5
	v_pk_add_f32 v[0:1], v[0:1], v[20:21]
	v_pk_add_f32 v[2:3], v[2:3], v[26:27]
	v_pk_add_f32 v[0:1], v[0:1], v[24:25]
	v_pk_add_f32 v[2:3], v[2:3], v[30:31]
	v_pk_add_f32 v[0:1], v[0:1], v[28:29]
	v_pk_add_f32 v[2:3], v[2:3], v[34:35]
	v_pk_add_f32 v[0:1], v[0:1], v[32:33]
	v_pk_add_f32 v[2:3], v[2:3], v[38:39]
	v_fma_f32 v7, -v5, v6, 1.0
	v_pk_add_f32 v[0:1], v[0:1], v[36:37]
	v_pk_add_f32 v[2:3], v[2:3], v[42:43]
	v_fmac_f32_e32 v6, v7, v6
	v_div_scale_f32 v7, vcc, 1.0, v4, 1.0
; __device__ __forceinline__ unsigned pk2(float lo, float hi) { unsigned r; asm volatile("v_cvt_pk_bf16_f32 %0, %1, %2" : "=v"(r) : "v"(lo), "v"(hi)); return r; }
; template <int GI> __device__ __forceinline__ void p4_dpass(const bf16_t* XB, const float* cache, bf16_t* Dm, int strip, int lane) {
;     ...
; #pragma unroll
;     for (int t = 0; t < 16; ++t) {
;         f32x4 s = rows[t];
; #pragma unroll
;         for (int j = 1; j < W; ++j) s += rows[t + j];
;         const int cnt = samp ? W : (W < pos0 + t + 1 ? W : pos0 + t + 1);
;         const f32x4 d = s * (1.0f / (float)cnt) - rows[t + W - 1];
;         u32x2 wv; wv.x = pk2(d[0], d[1]); wv.y = pk2(d[2], d[3]);
;         *(u32x2*)(Dm + (size_t)(tok0 + t) * 1024 + c) = wv;
;     }
	v_pk_add_f32 v[0:1], v[0:1], v[40:41]
	v_pk_add_f32 v[2:3], v[2:3], v[46:47]
	v_mul_f32_e32 v12, v7, v6
	v_pk_add_f32 v[0:1], v[0:1], v[44:45]
	v_pk_add_f32 v[2:3], v[2:3], v[50:51]
	v_fma_f32 v13, -v5, v12, v7
	v_pk_add_f32 v[0:1], v[0:1], v[48:49]
	v_pk_add_f32 v[2:3], v[2:3], v[54:55]
	v_fmac_f32_e32 v12, v13, v6
	v_pk_add_f32 v[0:1], v[0:1], v[52:53]
	v_pk_add_f32 v[2:3], v[2:3], v[58:59]
	v_fma_f32 v5, -v5, v12, v7
	v_pk_add_f32 v[0:1], v[0:1], v[56:57]
	v_pk_add_f32 v[2:3], v[2:3], v[146:147]
	v_div_fmas_f32 v5, v5, v6, v12
	v_and_b32_e32 v139, 0xffff0000, v139
	v_pk_add_f32 v[0:1], v[0:1], v[144:145]
	v_pk_add_f32 v[2:3], v[2:3], v[142:143]
	v_div_fixup_f32 v4, v5, v4, 1.0
	v_pk_add_f32 v[0:1], v[0:1], v[140:141]
	v_pk_add_f32 v[2:3], v[2:3], v[138:139]
	v_cndmask_b32_e64 v4, v4, v149, s[8:9]
	v_xor_b32_e32 v7, 0x80000000, v139
	v_xor_b32_e32 v6, 0x80000000, v138
	v_pk_add_f32 v[0:1], v[0:1], v[136:137]
	v_pk_fma_f32 v[2:3], v[4:5], v[2:3], v[6:7] op_sel_hi:[0,1,1]
	v_xor_b32_e32 v7, 0x80000000, v137
	v_xor_b32_e32 v6, 0x80000000, v136
	s_or_b32 s22, s27, 3
	v_pk_fma_f32 v[0:1], v[4:5], v[0:1], v[6:7] op_sel_hi:[0,1,1]
	s_min_u32 s22, s22, 15
	v_cvt_pk_bf16_f32 v0, v0, v1
	v_cvt_pk_bf16_f32 v1, v2, v3
	v_lshl_add_u64 v[2:3], v[70:71], 0, s[72:73]
	s_add_i32 s22, s22, 1
	global_store_dwordx2 v[2:3], v[0:1], off
	v_pk_add_f32 v[2:3], v[10:11], v[18:19]
	v_cvt_f32_ubyte0_e32 v4, s22
	v_pk_add_f32 v[0:1], v[8:9], v[16:17]
	v_pk_add_f32 v[2:3], v[2:3], v[22:23]
	v_div_scale_f32 v5, s[34:35], v4, v4, 1.0
	v_pk_add_f32 v[0:1], v[0:1], v[20:21]
	v_pk_add_f32 v[2:3], v[2:3], v[26:27]
	v_rcp_f32_e32 v6, v5
	v_pk_add_f32 v[0:1], v[0:1], v[24:25]
	v_pk_add_f32 v[2:3], v[2:3], v[30:31]
	v_pk_add_f32 v[0:1], v[0:1], v[28:29]
	v_pk_add_f32 v[2:3], v[2:3], v[34:35]
	v_pk_add_f32 v[0:1], v[0:1], v[32:33]
	v_pk_add_f32 v[2:3], v[2:3], v[38:39]
	v_pk_add_f32 v[0:1], v[0:1], v[36:37]
	v_pk_add_f32 v[2:3], v[2:3], v[42:43]
	v_fma_f32 v7, -v5, v6, 1.0
	v_pk_add_f32 v[0:1], v[0:1], v[40:41]
	v_pk_add_f32 v[2:3], v[2:3], v[46:47]
	v_fmac_f32_e32 v6, v7, v6
	v_div_scale_f32 v7, vcc, 1.0, v4, 1.0
	v_pk_add_f32 v[0:1], v[0:1], v[44:45]
	v_pk_add_f32 v[2:3], v[2:3], v[50:51]
	v_mul_f32_e32 v8, v7, v6
	v_pk_add_f32 v[0:1], v[0:1], v[48:49]
	v_pk_add_f32 v[2:3], v[2:3], v[54:55]
	v_fma_f32 v9, -v5, v8, v7
	v_pk_add_f32 v[0:1], v[0:1], v[52:53]
	v_pk_add_f32 v[2:3], v[2:3], v[58:59]
	v_fmac_f32_e32 v8, v9, v6
	v_pk_add_f32 v[0:1], v[0:1], v[56:57]
	v_pk_add_f32 v[2:3], v[2:3], v[146:147]
	v_fma_f32 v5, -v5, v8, v7
	v_pk_add_f32 v[0:1], v[0:1], v[144:145]
	v_pk_add_f32 v[2:3], v[2:3], v[142:143]
	v_div_fmas_f32 v5, v5, v6, v8
	v_lshlrev_b32_e32 v132, 16, v134
	v_and_b32_e32 v133, 0xffff0000, v134
	v_lshlrev_b32_e32 v134, 16, v135
	v_and_b32_e32 v135, 0xffff0000, v135
	v_pk_add_f32 v[0:1], v[0:1], v[140:141]
	v_pk_add_f32 v[2:3], v[2:3], v[138:139]
	v_div_fixup_f32 v4, v5, v4, 1.0
	v_pk_add_f32 v[0:1], v[0:1], v[136:137]
	v_pk_add_f32 v[2:3], v[2:3], v[134:135]
	v_cndmask_b32_e64 v4, v4, v149, s[8:9]
	v_xor_b32_e32 v7, 0x80000000, v135
	v_xor_b32_e32 v6, 0x80000000, v134
	v_pk_add_f32 v[0:1], v[0:1], v[132:133]
	v_pk_fma_f32 v[2:3], v[4:5], v[2:3], v[6:7] op_sel_hi:[0,1,1]
	v_xor_b32_e32 v7, 0x80000000, v133
	v_xor_b32_e32 v6, 0x80000000, v132
	s_or_b32 s22, s27, 4
	v_pk_fma_f32 v[0:1], v[4:5], v[0:1], v[6:7] op_sel_hi:[0,1,1]
	s_min_u32 s22, s22, 15
	v_cvt_pk_bf16_f32 v0, v0, v1
	v_cvt_pk_bf16_f32 v1, v2, v3
	v_lshl_add_u64 v[2:3], v[70:71], 0, s[70:71]
	s_add_i32 s22, s22, 1
	global_store_dwordx2 v[2:3], v[0:1], off
	v_pk_add_f32 v[2:3], v[18:19], v[22:23]
	v_cvt_f32_ubyte0_e32 v4, s22
	v_pk_add_f32 v[0:1], v[16:17], v[20:21]
	v_pk_add_f32 v[2:3], v[2:3], v[26:27]
	v_div_scale_f32 v5, s[34:35], v4, v4, 1.0
	v_pk_add_f32 v[0:1], v[0:1], v[24:25]
	v_pk_add_f32 v[2:3], v[2:3], v[30:31]
	v_rcp_f32_e32 v6, v5
	v_pk_add_f32 v[0:1], v[0:1], v[28:29]
	v_pk_add_f32 v[2:3], v[2:3], v[34:35]
	v_pk_add_f32 v[0:1], v[0:1], v[32:33]
	v_pk_add_f32 v[2:3], v[2:3], v[38:39]
	v_pk_add_f32 v[0:1], v[0:1], v[36:37]
	v_pk_add_f32 v[2:3], v[2:3], v[42:43]
	v_pk_add_f32 v[0:1], v[0:1], v[40:41]
	v_pk_add_f32 v[2:3], v[2:3], v[46:47]
	v_fma_f32 v7, -v5, v6, 1.0
	v_pk_add_f32 v[0:1], v[0:1], v[44:45]
	v_pk_add_f32 v[2:3], v[2:3], v[50:51]
	v_fmac_f32_e32 v6, v7, v6
	v_div_scale_f32 v7, vcc, 1.0, v4, 1.0
	v_pk_add_f32 v[0:1], v[0:1], v[48:49]
	v_pk_add_f32 v[2:3], v[2:3], v[54:55]
	v_mul_f32_e32 v8, v7, v6
	v_pk_add_f32 v[0:1], v[0:1], v[52:53]
	v_pk_add_f32 v[2:3], v[2:3], v[58:59]
	v_fma_f32 v9, -v5, v8, v7
	v_pk_add_f32 v[0:1], v[0:1], v[56:57]
	v_pk_add_f32 v[2:3], v[2:3], v[146:147]
	v_fmac_f32_e32 v8, v9, v6
	v_pk_add_f32 v[0:1], v[0:1], v[144:145]
	v_pk_add_f32 v[2:3], v[2:3], v[142:143]
	v_fma_f32 v5, -v5, v8, v7
	v_pk_add_f32 v[0:1], v[0:1], v[140:141]
	v_pk_add_f32 v[2:3], v[2:3], v[138:139]
	v_div_fmas_f32 v5, v5, v6, v8
	v_lshlrev_b32_e32 v128, 16, v130
	v_and_b32_e32 v129, 0xffff0000, v130
	v_lshlrev_b32_e32 v130, 16, v131
	v_and_b32_e32 v131, 0xffff0000, v131
	v_pk_add_f32 v[0:1], v[0:1], v[136:137]
	v_pk_add_f32 v[2:3], v[2:3], v[134:135]
	v_div_fixup_f32 v4, v5, v4, 1.0
	v_pk_add_f32 v[0:1], v[0:1], v[132:133]
	v_pk_add_f32 v[2:3], v[2:3], v[130:131]
	v_cndmask_b32_e64 v4, v4, v149, s[8:9]
	v_xor_b32_e32 v7, 0x80000000, v131
	v_xor_b32_e32 v6, 0x80000000, v130
	v_pk_add_f32 v[0:1], v[0:1], v[128:129]
	v_pk_fma_f32 v[2:3], v[4:5], v[2:3], v[6:7] op_sel_hi:[0,1,1]
	v_xor_b32_e32 v7, 0x80000000, v129
	v_xor_b32_e32 v6, 0x80000000, v128
	s_or_b32 s22, s27, 5
	v_pk_fma_f32 v[0:1], v[4:5], v[0:1], v[6:7] op_sel_hi:[0,1,1]
	s_min_u32 s22, s22, 15
	v_cvt_pk_bf16_f32 v0, v0, v1
; __device__ __forceinline__ unsigned pk2(float lo, float hi) { unsigned r; asm volatile("v_cvt_pk_bf16_f32 %0, %1, %2" : "=v"(r) : "v"(lo), "v"(hi)); return r; }
; template <int GI> __device__ __forceinline__ void p4_dpass(const bf16_t* XB, const float* cache, bf16_t* Dm, int strip, int lane) {
;     ...
; #pragma unroll
;     for (int t = 0; t < 16; ++t) {
;         f32x4 s = rows[t];
; #pragma unroll
;         for (int j = 1; j < W; ++j) s += rows[t + j];
;         const int cnt = samp ? W : (W < pos0 + t + 1 ? W : pos0 + t + 1);
;         const f32x4 d = s * (1.0f / (float)cnt) - rows[t + W - 1];
;         u32x2 wv; wv.x = pk2(d[0], d[1]); wv.y = pk2(d[2], d[3]);
;         *(u32x2*)(Dm + (size_t)(tok0 + t) * 1024 + c) = wv;
;     }
	v_cvt_pk_bf16_f32 v1, v2, v3
	v_lshl_add_u64 v[2:3], v[70:71], 0, s[68:69]
	s_add_i32 s22, s22, 1
	global_store_dwordx2 v[2:3], v[0:1], off
	v_pk_add_f32 v[2:3], v[22:23], v[26:27]
	v_cvt_f32_ubyte0_e32 v4, s22
	v_pk_add_f32 v[0:1], v[20:21], v[24:25]
	v_pk_add_f32 v[2:3], v[2:3], v[30:31]
	v_div_scale_f32 v5, s[34:35], v4, v4, 1.0
	v_pk_add_f32 v[0:1], v[0:1], v[28:29]
	v_pk_add_f32 v[2:3], v[2:3], v[34:35]
	v_rcp_f32_e32 v6, v5
	v_pk_add_f32 v[0:1], v[0:1], v[32:33]
	v_pk_add_f32 v[2:3], v[2:3], v[38:39]
	v_pk_add_f32 v[0:1], v[0:1], v[36:37]
	v_pk_add_f32 v[2:3], v[2:3], v[42:43]
	v_pk_add_f32 v[0:1], v[0:1], v[40:41]
	v_pk_add_f32 v[2:3], v[2:3], v[46:47]
	v_pk_add_f32 v[0:1], v[0:1], v[44:45]
	v_pk_add_f32 v[2:3], v[2:3], v[50:51]
	v_fma_f32 v7, -v5, v6, 1.0
	v_pk_add_f32 v[0:1], v[0:1], v[48:49]
	v_pk_add_f32 v[2:3], v[2:3], v[54:55]
	v_fmac_f32_e32 v6, v7, v6
	v_div_scale_f32 v7, vcc, 1.0, v4, 1.0
	v_pk_add_f32 v[0:1], v[0:1], v[52:53]
	v_pk_add_f32 v[2:3], v[2:3], v[58:59]
	v_mul_f32_e32 v8, v7, v6
	v_pk_add_f32 v[0:1], v[0:1], v[56:57]
	v_pk_add_f32 v[2:3], v[2:3], v[146:147]
	v_fma_f32 v9, -v5, v8, v7
	v_pk_add_f32 v[0:1], v[0:1], v[144:145]
	v_pk_add_f32 v[2:3], v[2:3], v[142:143]
	v_fmac_f32_e32 v8, v9, v6
	v_pk_add_f32 v[0:1], v[0:1], v[140:141]
	v_pk_add_f32 v[2:3], v[2:3], v[138:139]
	v_fma_f32 v5, -v5, v8, v7
	v_pk_add_f32 v[0:1], v[0:1], v[136:137]
	v_pk_add_f32 v[2:3], v[2:3], v[134:135]
	v_div_fmas_f32 v5, v5, v6, v8
	v_lshlrev_b32_e32 v124, 16, v126
	v_and_b32_e32 v125, 0xffff0000, v126
	v_lshlrev_b32_e32 v126, 16, v127
	v_and_b32_e32 v127, 0xffff0000, v127
	v_pk_add_f32 v[0:1], v[0:1], v[132:133]
	v_pk_add_f32 v[2:3], v[2:3], v[130:131]
	v_div_fixup_f32 v4, v5, v4, 1.0
	v_pk_add_f32 v[0:1], v[0:1], v[128:129]
	v_pk_add_f32 v[2:3], v[2:3], v[126:127]
	v_cndmask_b32_e64 v4, v4, v149, s[8:9]
	v_xor_b32_e32 v7, 0x80000000, v127
	v_xor_b32_e32 v6, 0x80000000, v126
	v_pk_add_f32 v[0:1], v[0:1], v[124:125]
	v_pk_fma_f32 v[2:3], v[4:5], v[2:3], v[6:7] op_sel_hi:[0,1,1]
	v_xor_b32_e32 v7, 0x80000000, v125
	v_xor_b32_e32 v6, 0x80000000, v124
	s_or_b32 s22, s27, 6
	v_pk_fma_f32 v[0:1], v[4:5], v[0:1], v[6:7] op_sel_hi:[0,1,1]
	s_min_u32 s22, s22, 15
	v_cvt_pk_bf16_f32 v0, v0, v1
	v_cvt_pk_bf16_f32 v1, v2, v3
	v_lshl_add_u64 v[2:3], v[70:71], 0, s[66:67]
	s_add_i32 s22, s22, 1
	global_store_dwordx2 v[2:3], v[0:1], off
	v_pk_add_f32 v[2:3], v[26:27], v[30:31]
	v_cvt_f32_ubyte0_e32 v4, s22
	v_pk_add_f32 v[0:1], v[24:25], v[28:29]
	v_pk_add_f32 v[2:3], v[2:3], v[34:35]
	v_div_scale_f32 v5, s[34:35], v4, v4, 1.0
	v_pk_add_f32 v[0:1], v[0:1], v[32:33]
	v_pk_add_f32 v[2:3], v[2:3], v[38:39]
	v_rcp_f32_e32 v6, v5
	v_pk_add_f32 v[0:1], v[0:1], v[36:37]
	v_pk_add_f32 v[2:3], v[2:3], v[42:43]
	v_pk_add_f32 v[0:1], v[0:1], v[40:41]
	v_pk_add_f32 v[2:3], v[2:3], v[46:47]
	v_pk_add_f32 v[0:1], v[0:1], v[44:45]
	v_pk_add_f32 v[2:3], v[2:3], v[50:51]
	v_pk_add_f32 v[0:1], v[0:1], v[48:49]
	v_pk_add_f32 v[2:3], v[2:3], v[54:55]
	v_fma_f32 v7, -v5, v6, 1.0
	v_pk_add_f32 v[0:1], v[0:1], v[52:53]
	v_pk_add_f32 v[2:3], v[2:3], v[58:59]
	v_fmac_f32_e32 v6, v7, v6
	v_div_scale_f32 v7, vcc, 1.0, v4, 1.0
	v_pk_add_f32 v[0:1], v[0:1], v[56:57]
	v_pk_add_f32 v[2:3], v[2:3], v[146:147]
	v_mul_f32_e32 v8, v7, v6
	v_pk_add_f32 v[0:1], v[0:1], v[144:145]
	v_pk_add_f32 v[2:3], v[2:3], v[142:143]
	v_fma_f32 v9, -v5, v8, v7
	v_pk_add_f32 v[0:1], v[0:1], v[140:141]
	v_pk_add_f32 v[2:3], v[2:3], v[138:139]
	v_fmac_f32_e32 v8, v9, v6
	v_pk_add_f32 v[0:1], v[0:1], v[136:137]
	v_pk_add_f32 v[2:3], v[2:3], v[134:135]
	v_fma_f32 v5, -v5, v8, v7
	v_pk_add_f32 v[0:1], v[0:1], v[132:133]
	v_pk_add_f32 v[2:3], v[2:3], v[130:131]
	v_div_fmas_f32 v5, v5, v6, v8
	v_lshlrev_b32_e32 v120, 16, v122
	v_and_b32_e32 v121, 0xffff0000, v122
	v_lshlrev_b32_e32 v122, 16, v123
	v_and_b32_e32 v123, 0xffff0000, v123
	v_pk_add_f32 v[0:1], v[0:1], v[128:129]
	v_pk_add_f32 v[2:3], v[2:3], v[126:127]
	v_div_fixup_f32 v4, v5, v4, 1.0
	v_pk_add_f32 v[0:1], v[0:1], v[124:125]
	v_pk_add_f32 v[2:3], v[2:3], v[122:123]
	v_cndmask_b32_e64 v4, v4, v149, s[8:9]
	v_xor_b32_e32 v7, 0x80000000, v123
	v_xor_b32_e32 v6, 0x80000000, v122
	v_pk_add_f32 v[0:1], v[0:1], v[120:121]
	v_pk_fma_f32 v[2:3], v[4:5], v[2:3], v[6:7] op_sel_hi:[0,1,1]
	v_xor_b32_e32 v7, 0x80000000, v121
	v_xor_b32_e32 v6, 0x80000000, v120
	s_or_b32 s22, s27, 7
	v_pk_fma_f32 v[0:1], v[4:5], v[0:1], v[6:7] op_sel_hi:[0,1,1]
	s_min_u32 s22, s22, 15
	v_cvt_pk_bf16_f32 v0, v0, v1
	v_cvt_pk_bf16_f32 v1, v2, v3
	v_lshl_add_u64 v[2:3], v[70:71], 0, s[64:65]
	s_add_i32 s22, s22, 1
	global_store_dwordx2 v[2:3], v[0:1], off
	v_pk_add_f32 v[2:3], v[30:31], v[34:35]
	v_cvt_f32_ubyte0_e32 v4, s22
	v_pk_add_f32 v[0:1], v[28:29], v[32:33]
	v_pk_add_f32 v[2:3], v[2:3], v[38:39]
	v_div_scale_f32 v5, s[34:35], v4, v4, 1.0
	v_pk_add_f32 v[0:1], v[0:1], v[36:37]
	v_pk_add_f32 v[2:3], v[2:3], v[42:43]
	v_rcp_f32_e32 v6, v5
	v_pk_add_f32 v[0:1], v[0:1], v[40:41]
	v_pk_add_f32 v[2:3], v[2:3], v[46:47]
	v_pk_add_f32 v[0:1], v[0:1], v[44:45]
	v_pk_add_f32 v[2:3], v[2:3], v[50:51]
	v_pk_add_f32 v[0:1], v[0:1], v[48:49]
	v_pk_add_f32 v[2:3], v[2:3], v[54:55]
	v_pk_add_f32 v[0:1], v[0:1], v[52:53]
	v_pk_add_f32 v[2:3], v[2:3], v[58:59]
	v_fma_f32 v7, -v5, v6, 1.0
	v_pk_add_f32 v[0:1], v[0:1], v[56:57]
	v_pk_add_f32 v[2:3], v[2:3], v[146:147]
	v_fmac_f32_e32 v6, v7, v6
	v_div_scale_f32 v7, vcc, 1.0, v4, 1.0
	v_pk_add_f32 v[0:1], v[0:1], v[144:145]
	v_pk_add_f32 v[2:3], v[2:3], v[142:143]
	v_mul_f32_e32 v8, v7, v6
	v_pk_add_f32 v[0:1], v[0:1], v[140:141]
	v_pk_add_f32 v[2:3], v[2:3], v[138:139]
	v_fma_f32 v9, -v5, v8, v7
	v_pk_add_f32 v[0:1], v[0:1], v[136:137]
; __device__ __forceinline__ unsigned pk2(float lo, float hi) { unsigned r; asm volatile("v_cvt_pk_bf16_f32 %0, %1, %2" : "=v"(r) : "v"(lo), "v"(hi)); return r; }
; __device__ __forceinline__ float bf_lo(unsigned w) { return __uint_as_float(w << 16); }
; __device__ __forceinline__ float bf_hi(unsigned w) { return __uint_as_float(w & 0xffff0000u); }
; template <int GI> __device__ __forceinline__ void p4_dpass(const bf16_t* XB, const float* cache, bf16_t* Dm, int strip, int lane) {
;     ...
;         if (i >= W - 1 || pos0 != 0) { const u32x2 w = *(const u32x2*)(XB + (size_t)(tok0 - (W - 1) + i) * 1024 + c); rows[i] = (f32x4){bf_lo(w.x), bf_hi(w.x), bf_lo(w.y), bf_hi(w.y)}; }
;         else if (samp) rows[i] = *(const f32x4*)(cache + ((size_t)b * 15 + 15 - (W - 1) + i) * 1024 + c);
;         else rows[i] = (f32x4){0.f, 0.f, 0.f, 0.f};
;     }
; #pragma unroll
;     for (int t = 0; t < 16; ++t) {
;         f32x4 s = rows[t];
; #pragma unroll
;         for (int j = 1; j < W; ++j) s += rows[t + j];
;         const int cnt = samp ? W : (W < pos0 + t + 1 ? W : pos0 + t + 1);
;         const f32x4 d = s * (1.0f / (float)cnt) - rows[t + W - 1];
;         u32x2 wv; wv.x = pk2(d[0], d[1]); wv.y = pk2(d[2], d[3]);
;         *(u32x2*)(Dm + (size_t)(tok0 + t) * 1024 + c) = wv;
	v_pk_add_f32 v[2:3], v[2:3], v[134:135]
	v_fmac_f32_e32 v8, v9, v6
	v_pk_add_f32 v[0:1], v[0:1], v[132:133]
	v_pk_add_f32 v[2:3], v[2:3], v[130:131]
	v_fma_f32 v5, -v5, v8, v7
	v_pk_add_f32 v[0:1], v[0:1], v[128:129]
	v_pk_add_f32 v[2:3], v[2:3], v[126:127]
	v_div_fmas_f32 v5, v5, v6, v8
	v_lshlrev_b32_e32 v116, 16, v118
	v_and_b32_e32 v117, 0xffff0000, v118
	v_lshlrev_b32_e32 v118, 16, v119
	v_and_b32_e32 v119, 0xffff0000, v119
	v_pk_add_f32 v[0:1], v[0:1], v[124:125]
	v_pk_add_f32 v[2:3], v[2:3], v[122:123]
	v_div_fixup_f32 v4, v5, v4, 1.0
	v_pk_add_f32 v[0:1], v[0:1], v[120:121]
	v_pk_add_f32 v[2:3], v[2:3], v[118:119]
	v_cndmask_b32_e64 v4, v4, v149, s[8:9]
	v_xor_b32_e32 v7, 0x80000000, v119
	v_xor_b32_e32 v6, 0x80000000, v118
	v_pk_add_f32 v[0:1], v[0:1], v[116:117]
	v_pk_fma_f32 v[2:3], v[4:5], v[2:3], v[6:7] op_sel_hi:[0,1,1]
	v_xor_b32_e32 v7, 0x80000000, v117
	v_xor_b32_e32 v6, 0x80000000, v116
	s_or_b32 s22, s27, 8
	v_pk_fma_f32 v[0:1], v[4:5], v[0:1], v[6:7] op_sel_hi:[0,1,1]
	s_min_u32 s22, s22, 15
	v_cvt_pk_bf16_f32 v0, v0, v1
	v_cvt_pk_bf16_f32 v1, v2, v3
	v_lshl_add_u64 v[2:3], v[70:71], 0, s[62:63]
	s_add_i32 s22, s22, 1
	global_store_dwordx2 v[2:3], v[0:1], off
	v_pk_add_f32 v[2:3], v[34:35], v[38:39]
	v_cvt_f32_ubyte0_e32 v4, s22
	v_pk_add_f32 v[0:1], v[32:33], v[36:37]
	v_pk_add_f32 v[2:3], v[2:3], v[42:43]
	v_div_scale_f32 v5, s[34:35], v4, v4, 1.0
	v_pk_add_f32 v[0:1], v[0:1], v[40:41]
	v_pk_add_f32 v[2:3], v[2:3], v[46:47]
	v_rcp_f32_e32 v6, v5
	v_pk_add_f32 v[0:1], v[0:1], v[44:45]
	v_pk_add_f32 v[2:3], v[2:3], v[50:51]
	v_pk_add_f32 v[0:1], v[0:1], v[48:49]
	v_pk_add_f32 v[2:3], v[2:3], v[54:55]
	v_pk_add_f32 v[0:1], v[0:1], v[52:53]
	v_pk_add_f32 v[2:3], v[2:3], v[58:59]
	v_pk_add_f32 v[0:1], v[0:1], v[56:57]
	v_pk_add_f32 v[2:3], v[2:3], v[146:147]
	v_fma_f32 v7, -v5, v6, 1.0
	v_pk_add_f32 v[0:1], v[0:1], v[144:145]
	v_pk_add_f32 v[2:3], v[2:3], v[142:143]
	v_fmac_f32_e32 v6, v7, v6
	v_div_scale_f32 v7, vcc, 1.0, v4, 1.0
	v_pk_add_f32 v[0:1], v[0:1], v[140:141]
	v_pk_add_f32 v[2:3], v[2:3], v[138:139]
	v_mul_f32_e32 v8, v7, v6
	v_pk_add_f32 v[0:1], v[0:1], v[136:137]
	v_pk_add_f32 v[2:3], v[2:3], v[134:135]
	v_fma_f32 v9, -v5, v8, v7
	v_pk_add_f32 v[0:1], v[0:1], v[132:133]
	v_pk_add_f32 v[2:3], v[2:3], v[130:131]
	v_fmac_f32_e32 v8, v9, v6
	v_pk_add_f32 v[0:1], v[0:1], v[128:129]
	v_pk_add_f32 v[2:3], v[2:3], v[126:127]
	v_fma_f32 v5, -v5, v8, v7
	v_pk_add_f32 v[0:1], v[0:1], v[124:125]
	v_pk_add_f32 v[2:3], v[2:3], v[122:123]
	v_div_fmas_f32 v5, v5, v6, v8
	v_lshlrev_b32_e32 v112, 16, v114
	v_and_b32_e32 v113, 0xffff0000, v114
	v_lshlrev_b32_e32 v114, 16, v115
	v_and_b32_e32 v115, 0xffff0000, v115
	v_pk_add_f32 v[0:1], v[0:1], v[120:121]
	v_pk_add_f32 v[2:3], v[2:3], v[118:119]
	v_div_fixup_f32 v4, v5, v4, 1.0
	v_pk_add_f32 v[0:1], v[0:1], v[116:117]
	v_pk_add_f32 v[2:3], v[2:3], v[114:115]
	v_cndmask_b32_e64 v4, v4, v149, s[8:9]
	v_xor_b32_e32 v7, 0x80000000, v115
	v_xor_b32_e32 v6, 0x80000000, v114
	v_pk_add_f32 v[0:1], v[0:1], v[112:113]
	v_pk_fma_f32 v[2:3], v[4:5], v[2:3], v[6:7] op_sel_hi:[0,1,1]
	v_xor_b32_e32 v7, 0x80000000, v113
	v_xor_b32_e32 v6, 0x80000000, v112
	s_or_b32 s22, s27, 9
	v_pk_fma_f32 v[0:1], v[4:5], v[0:1], v[6:7] op_sel_hi:[0,1,1]
	s_min_u32 s22, s22, 15
	v_cvt_pk_bf16_f32 v0, v0, v1
	v_cvt_pk_bf16_f32 v1, v2, v3
	v_lshl_add_u64 v[2:3], v[70:71], 0, s[60:61]
	s_add_i32 s22, s22, 1
	global_store_dwordx2 v[2:3], v[0:1], off
	v_pk_add_f32 v[2:3], v[38:39], v[42:43]
	v_cvt_f32_ubyte0_e32 v4, s22
	v_pk_add_f32 v[0:1], v[36:37], v[40:41]
	v_pk_add_f32 v[2:3], v[2:3], v[46:47]
	v_div_scale_f32 v5, s[34:35], v4, v4, 1.0
	v_pk_add_f32 v[0:1], v[0:1], v[44:45]
	v_pk_add_f32 v[2:3], v[2:3], v[50:51]
	v_rcp_f32_e32 v6, v5
	v_pk_add_f32 v[0:1], v[0:1], v[48:49]
	v_pk_add_f32 v[2:3], v[2:3], v[54:55]
	v_pk_add_f32 v[0:1], v[0:1], v[52:53]
	v_pk_add_f32 v[2:3], v[2:3], v[58:59]
	v_pk_add_f32 v[0:1], v[0:1], v[56:57]
	v_pk_add_f32 v[2:3], v[2:3], v[146:147]
	v_pk_add_f32 v[0:1], v[0:1], v[144:145]
	v_pk_add_f32 v[2:3], v[2:3], v[142:143]
	v_fma_f32 v7, -v5, v6, 1.0
	v_pk_add_f32 v[0:1], v[0:1], v[140:141]
	v_pk_add_f32 v[2:3], v[2:3], v[138:139]
	v_fmac_f32_e32 v6, v7, v6
	v_div_scale_f32 v7, vcc, 1.0, v4, 1.0
	v_pk_add_f32 v[0:1], v[0:1], v[136:137]
	v_pk_add_f32 v[2:3], v[2:3], v[134:135]
	v_mul_f32_e32 v8, v7, v6
	v_pk_add_f32 v[0:1], v[0:1], v[132:133]
	v_pk_add_f32 v[2:3], v[2:3], v[130:131]
	v_fma_f32 v9, -v5, v8, v7
	v_pk_add_f32 v[0:1], v[0:1], v[128:129]
	v_pk_add_f32 v[2:3], v[2:3], v[126:127]
	v_fmac_f32_e32 v8, v9, v6
	v_pk_add_f32 v[0:1], v[0:1], v[124:125]
	v_pk_add_f32 v[2:3], v[2:3], v[122:123]
	v_fma_f32 v5, -v5, v8, v7
	v_pk_add_f32 v[0:1], v[0:1], v[120:121]
	v_pk_add_f32 v[2:3], v[2:3], v[118:119]
	v_div_fmas_f32 v5, v5, v6, v8
	v_lshlrev_b32_e32 v108, 16, v110
	v_and_b32_e32 v109, 0xffff0000, v110
	v_lshlrev_b32_e32 v110, 16, v111
	v_and_b32_e32 v111, 0xffff0000, v111
	v_pk_add_f32 v[0:1], v[0:1], v[116:117]
	v_pk_add_f32 v[2:3], v[2:3], v[114:115]
	v_div_fixup_f32 v4, v5, v4, 1.0
	v_pk_add_f32 v[0:1], v[0:1], v[112:113]
	v_pk_add_f32 v[2:3], v[2:3], v[110:111]
	v_cndmask_b32_e64 v4, v4, v149, s[8:9]
	v_xor_b32_e32 v7, 0x80000000, v111
	v_xor_b32_e32 v6, 0x80000000, v110
	v_pk_add_f32 v[0:1], v[0:1], v[108:109]
	v_pk_fma_f32 v[2:3], v[4:5], v[2:3], v[6:7] op_sel_hi:[0,1,1]
	v_xor_b32_e32 v7, 0x80000000, v109
	v_xor_b32_e32 v6, 0x80000000, v108
	s_or_b32 s22, s27, 10
	v_pk_fma_f32 v[0:1], v[4:5], v[0:1], v[6:7] op_sel_hi:[0,1,1]
	s_min_u32 s22, s22, 15
	v_cvt_pk_bf16_f32 v0, v0, v1
	v_cvt_pk_bf16_f32 v1, v2, v3
	v_lshl_add_u64 v[2:3], v[70:71], 0, s[58:59]
	s_add_i32 s22, s22, 1
; __device__ __forceinline__ unsigned pk2(float lo, float hi) { unsigned r; asm volatile("v_cvt_pk_bf16_f32 %0, %1, %2" : "=v"(r) : "v"(lo), "v"(hi)); return r; }
; __device__ __forceinline__ float bf_lo(unsigned w) { return __uint_as_float(w << 16); }
; __device__ __forceinline__ float bf_hi(unsigned w) { return __uint_as_float(w & 0xffff0000u); }
; template <int GI> __device__ __forceinline__ void p4_dpass(const bf16_t* XB, const float* cache, bf16_t* Dm, int strip, int lane) {
;     ...
;         if (i >= W - 1 || pos0 != 0) { const u32x2 w = *(const u32x2*)(XB + (size_t)(tok0 - (W - 1) + i) * 1024 + c); rows[i] = (f32x4){bf_lo(w.x), bf_hi(w.x), bf_lo(w.y), bf_hi(w.y)}; }
;         else if (samp) rows[i] = *(const f32x4*)(cache + ((size_t)b * 15 + 15 - (W - 1) + i) * 1024 + c);
;         else rows[i] = (f32x4){0.f, 0.f, 0.f, 0.f};
;     }
; #pragma unroll
;     for (int t = 0; t < 16; ++t) {
;         f32x4 s = rows[t];
; #pragma unroll
;         for (int j = 1; j < W; ++j) s += rows[t + j];
;         const int cnt = samp ? W : (W < pos0 + t + 1 ? W : pos0 + t + 1);
;         const f32x4 d = s * (1.0f / (float)cnt) - rows[t + W - 1];
;         u32x2 wv; wv.x = pk2(d[0], d[1]); wv.y = pk2(d[2], d[3]);
;         *(u32x2*)(Dm + (size_t)(tok0 + t) * 1024 + c) = wv;
	global_store_dwordx2 v[2:3], v[0:1], off
	v_pk_add_f32 v[2:3], v[42:43], v[46:47]
	v_cvt_f32_ubyte0_e32 v4, s22
	v_pk_add_f32 v[0:1], v[40:41], v[44:45]
	v_pk_add_f32 v[2:3], v[2:3], v[50:51]
	v_div_scale_f32 v5, s[34:35], v4, v4, 1.0
	v_pk_add_f32 v[0:1], v[0:1], v[48:49]
	v_pk_add_f32 v[2:3], v[2:3], v[54:55]
	v_rcp_f32_e32 v6, v5
	v_pk_add_f32 v[0:1], v[0:1], v[52:53]
	v_pk_add_f32 v[2:3], v[2:3], v[58:59]
	v_pk_add_f32 v[0:1], v[0:1], v[56:57]
	v_pk_add_f32 v[2:3], v[2:3], v[146:147]
	v_pk_add_f32 v[0:1], v[0:1], v[144:145]
	v_pk_add_f32 v[2:3], v[2:3], v[142:143]
	v_pk_add_f32 v[0:1], v[0:1], v[140:141]
	v_pk_add_f32 v[2:3], v[2:3], v[138:139]
	v_fma_f32 v7, -v5, v6, 1.0
	v_pk_add_f32 v[0:1], v[0:1], v[136:137]
	v_pk_add_f32 v[2:3], v[2:3], v[134:135]
	v_fmac_f32_e32 v6, v7, v6
	v_div_scale_f32 v7, vcc, 1.0, v4, 1.0
	v_pk_add_f32 v[0:1], v[0:1], v[132:133]
	v_pk_add_f32 v[2:3], v[2:3], v[130:131]
	v_mul_f32_e32 v8, v7, v6
	v_pk_add_f32 v[0:1], v[0:1], v[128:129]
	v_pk_add_f32 v[2:3], v[2:3], v[126:127]
	v_fma_f32 v9, -v5, v8, v7
	v_pk_add_f32 v[0:1], v[0:1], v[124:125]
	v_pk_add_f32 v[2:3], v[2:3], v[122:123]
	v_fmac_f32_e32 v8, v9, v6
	v_pk_add_f32 v[0:1], v[0:1], v[120:121]
	v_pk_add_f32 v[2:3], v[2:3], v[118:119]
	v_fma_f32 v5, -v5, v8, v7
	v_pk_add_f32 v[0:1], v[0:1], v[116:117]
	v_pk_add_f32 v[2:3], v[2:3], v[114:115]
	v_div_fmas_f32 v5, v5, v6, v8
	v_lshlrev_b32_e32 v104, 16, v106
	v_and_b32_e32 v105, 0xffff0000, v106
	v_lshlrev_b32_e32 v106, 16, v107
	v_and_b32_e32 v107, 0xffff0000, v107
	v_pk_add_f32 v[0:1], v[0:1], v[112:113]
	v_pk_add_f32 v[2:3], v[2:3], v[110:111]
	v_div_fixup_f32 v4, v5, v4, 1.0
	v_pk_add_f32 v[0:1], v[0:1], v[108:109]
	v_pk_add_f32 v[2:3], v[2:3], v[106:107]
	v_cndmask_b32_e64 v4, v4, v149, s[8:9]
	v_xor_b32_e32 v7, 0x80000000, v107
	v_xor_b32_e32 v6, 0x80000000, v106
	v_pk_add_f32 v[0:1], v[0:1], v[104:105]
	v_pk_fma_f32 v[2:3], v[4:5], v[2:3], v[6:7] op_sel_hi:[0,1,1]
	v_xor_b32_e32 v7, 0x80000000, v105
	v_xor_b32_e32 v6, 0x80000000, v104
	s_or_b32 s22, s27, 11
	v_pk_fma_f32 v[0:1], v[4:5], v[0:1], v[6:7] op_sel_hi:[0,1,1]
	s_min_u32 s22, s22, 15
	v_cvt_pk_bf16_f32 v0, v0, v1
	v_cvt_pk_bf16_f32 v1, v2, v3
	v_lshl_add_u64 v[2:3], v[70:71], 0, s[56:57]
	s_add_i32 s22, s22, 1
	global_store_dwordx2 v[2:3], v[0:1], off
	v_pk_add_f32 v[2:3], v[46:47], v[50:51]
	v_cvt_f32_ubyte0_e32 v4, s22
	v_pk_add_f32 v[0:1], v[44:45], v[48:49]
	v_pk_add_f32 v[2:3], v[2:3], v[54:55]
	v_div_scale_f32 v5, s[34:35], v4, v4, 1.0
	v_pk_add_f32 v[0:1], v[0:1], v[52:53]
	v_pk_add_f32 v[2:3], v[2:3], v[58:59]
	v_rcp_f32_e32 v6, v5
	v_pk_add_f32 v[0:1], v[0:1], v[56:57]
	v_pk_add_f32 v[2:3], v[2:3], v[146:147]
	v_pk_add_f32 v[0:1], v[0:1], v[144:145]
	v_pk_add_f32 v[2:3], v[2:3], v[142:143]
	v_pk_add_f32 v[0:1], v[0:1], v[140:141]
	v_pk_add_f32 v[2:3], v[2:3], v[138:139]
	v_pk_add_f32 v[0:1], v[0:1], v[136:137]
	v_pk_add_f32 v[2:3], v[2:3], v[134:135]
	v_fma_f32 v7, -v5, v6, 1.0
	v_pk_add_f32 v[0:1], v[0:1], v[132:133]
	v_pk_add_f32 v[2:3], v[2:3], v[130:131]
	v_fmac_f32_e32 v6, v7, v6
	v_div_scale_f32 v7, vcc, 1.0, v4, 1.0
	v_pk_add_f32 v[0:1], v[0:1], v[128:129]
	v_pk_add_f32 v[2:3], v[2:3], v[126:127]
	v_mul_f32_e32 v8, v7, v6
	v_pk_add_f32 v[0:1], v[0:1], v[124:125]
	v_pk_add_f32 v[2:3], v[2:3], v[122:123]
	v_fma_f32 v9, -v5, v8, v7
	v_pk_add_f32 v[0:1], v[0:1], v[120:121]
	v_pk_add_f32 v[2:3], v[2:3], v[118:119]
	v_fmac_f32_e32 v8, v9, v6
	v_pk_add_f32 v[0:1], v[0:1], v[116:117]
	v_pk_add_f32 v[2:3], v[2:3], v[114:115]
	v_fma_f32 v5, -v5, v8, v7
	v_pk_add_f32 v[0:1], v[0:1], v[112:113]
	v_pk_add_f32 v[2:3], v[2:3], v[110:111]
	v_div_fmas_f32 v5, v5, v6, v8
	v_lshlrev_b32_e32 v100, 16, v102
	v_and_b32_e32 v101, 0xffff0000, v102
	v_lshlrev_b32_e32 v102, 16, v103
	v_and_b32_e32 v103, 0xffff0000, v103
	v_pk_add_f32 v[0:1], v[0:1], v[108:109]
	v_pk_add_f32 v[2:3], v[2:3], v[106:107]
	v_div_fixup_f32 v4, v5, v4, 1.0
	v_pk_add_f32 v[0:1], v[0:1], v[104:105]
	v_pk_add_f32 v[2:3], v[2:3], v[102:103]
	v_cndmask_b32_e64 v4, v4, v149, s[8:9]
	v_xor_b32_e32 v7, 0x80000000, v103
	v_xor_b32_e32 v6, 0x80000000, v102
	v_pk_add_f32 v[0:1], v[0:1], v[100:101]
	v_pk_fma_f32 v[2:3], v[4:5], v[2:3], v[6:7] op_sel_hi:[0,1,1]
	v_xor_b32_e32 v7, 0x80000000, v101
	v_xor_b32_e32 v6, 0x80000000, v100
	s_or_b32 s22, s27, 12
	v_pk_fma_f32 v[0:1], v[4:5], v[0:1], v[6:7] op_sel_hi:[0,1,1]
	s_min_u32 s22, s22, 15
	v_cvt_pk_bf16_f32 v0, v0, v1
	v_cvt_pk_bf16_f32 v1, v2, v3
	v_lshl_add_u64 v[2:3], v[70:71], 0, s[54:55]
	s_add_i32 s22, s22, 1
	global_store_dwordx2 v[2:3], v[0:1], off
	v_pk_add_f32 v[2:3], v[50:51], v[54:55]
	v_cvt_f32_ubyte0_e32 v4, s22
	v_pk_add_f32 v[0:1], v[48:49], v[52:53]
	v_pk_add_f32 v[2:3], v[2:3], v[58:59]
	v_div_scale_f32 v5, s[34:35], v4, v4, 1.0
	v_pk_add_f32 v[0:1], v[0:1], v[56:57]
	v_pk_add_f32 v[2:3], v[2:3], v[146:147]
	v_rcp_f32_e32 v6, v5
	v_pk_add_f32 v[0:1], v[0:1], v[144:145]
	v_pk_add_f32 v[2:3], v[2:3], v[142:143]
	v_pk_add_f32 v[0:1], v[0:1], v[140:141]
	v_pk_add_f32 v[2:3], v[2:3], v[138:139]
	v_pk_add_f32 v[0:1], v[0:1], v[136:137]
	v_pk_add_f32 v[2:3], v[2:3], v[134:135]
	v_pk_add_f32 v[0:1], v[0:1], v[132:133]
	v_pk_add_f32 v[2:3], v[2:3], v[130:131]
	v_fma_f32 v7, -v5, v6, 1.0
	v_pk_add_f32 v[0:1], v[0:1], v[128:129]
	v_pk_add_f32 v[2:3], v[2:3], v[126:127]
	v_fmac_f32_e32 v6, v7, v6
	v_div_scale_f32 v7, vcc, 1.0, v4, 1.0
	v_pk_add_f32 v[0:1], v[0:1], v[124:125]
	v_pk_add_f32 v[2:3], v[2:3], v[122:123]
	v_mul_f32_e32 v8, v7, v6
	v_pk_add_f32 v[0:1], v[0:1], v[120:121]
	v_pk_add_f32 v[2:3], v[2:3], v[118:119]
	v_fma_f32 v9, -v5, v8, v7
	v_pk_add_f32 v[0:1], v[0:1], v[116:117]
	v_pk_add_f32 v[2:3], v[2:3], v[114:115]
; __device__ __forceinline__ unsigned pk2(float lo, float hi) { unsigned r; asm volatile("v_cvt_pk_bf16_f32 %0, %1, %2" : "=v"(r) : "v"(lo), "v"(hi)); return r; }
; __device__ __forceinline__ float bf_lo(unsigned w) { return __uint_as_float(w << 16); }
; __device__ __forceinline__ float bf_hi(unsigned w) { return __uint_as_float(w & 0xffff0000u); }
; template <int GI> __device__ __forceinline__ void p4_dpass(const bf16_t* XB, const float* cache, bf16_t* Dm, int strip, int lane) {
;     ...
;         if (i >= W - 1 || pos0 != 0) { const u32x2 w = *(const u32x2*)(XB + (size_t)(tok0 - (W - 1) + i) * 1024 + c); rows[i] = (f32x4){bf_lo(w.x), bf_hi(w.x), bf_lo(w.y), bf_hi(w.y)}; }
;         else if (samp) rows[i] = *(const f32x4*)(cache + ((size_t)b * 15 + 15 - (W - 1) + i) * 1024 + c);
;         else rows[i] = (f32x4){0.f, 0.f, 0.f, 0.f};
;     }
; #pragma unroll
;     for (int t = 0; t < 16; ++t) {
;         f32x4 s = rows[t];
; #pragma unroll
;         for (int j = 1; j < W; ++j) s += rows[t + j];
;         const int cnt = samp ? W : (W < pos0 + t + 1 ? W : pos0 + t + 1);
;         const f32x4 d = s * (1.0f / (float)cnt) - rows[t + W - 1];
;         u32x2 wv; wv.x = pk2(d[0], d[1]); wv.y = pk2(d[2], d[3]);
;         *(u32x2*)(Dm + (size_t)(tok0 + t) * 1024 + c) = wv;
	v_fmac_f32_e32 v8, v9, v6
	v_pk_add_f32 v[0:1], v[0:1], v[112:113]
	v_pk_add_f32 v[2:3], v[2:3], v[110:111]
	v_fma_f32 v5, -v5, v8, v7
	v_pk_add_f32 v[0:1], v[0:1], v[108:109]
	v_pk_add_f32 v[2:3], v[2:3], v[106:107]
	v_div_fmas_f32 v5, v5, v6, v8
	v_lshlrev_b32_e32 v96, 16, v98
	v_and_b32_e32 v97, 0xffff0000, v98
	v_lshlrev_b32_e32 v98, 16, v99
	v_and_b32_e32 v99, 0xffff0000, v99
	v_pk_add_f32 v[0:1], v[0:1], v[104:105]
	v_pk_add_f32 v[2:3], v[2:3], v[102:103]
	v_div_fixup_f32 v4, v5, v4, 1.0
	v_pk_add_f32 v[0:1], v[0:1], v[100:101]
	v_pk_add_f32 v[2:3], v[2:3], v[98:99]
	v_cndmask_b32_e64 v4, v4, v149, s[8:9]
	v_xor_b32_e32 v7, 0x80000000, v99
	v_xor_b32_e32 v6, 0x80000000, v98
	v_pk_add_f32 v[0:1], v[0:1], v[96:97]
	v_pk_fma_f32 v[2:3], v[4:5], v[2:3], v[6:7] op_sel_hi:[0,1,1]
	v_xor_b32_e32 v7, 0x80000000, v97
	v_xor_b32_e32 v6, 0x80000000, v96
	s_or_b32 s22, s27, 13
	v_pk_fma_f32 v[0:1], v[4:5], v[0:1], v[6:7] op_sel_hi:[0,1,1]
	s_min_u32 s22, s22, 15
	v_cvt_pk_bf16_f32 v0, v0, v1
	v_cvt_pk_bf16_f32 v1, v2, v3
	v_lshl_add_u64 v[2:3], v[70:71], 0, s[52:53]
	s_add_i32 s22, s22, 1
	global_store_dwordx2 v[2:3], v[0:1], off
	v_pk_add_f32 v[2:3], v[54:55], v[58:59]
	v_cvt_f32_ubyte0_e32 v4, s22
	v_pk_add_f32 v[0:1], v[52:53], v[56:57]
	v_pk_add_f32 v[2:3], v[2:3], v[146:147]
	v_div_scale_f32 v5, s[34:35], v4, v4, 1.0
	v_pk_add_f32 v[0:1], v[0:1], v[144:145]
	v_pk_add_f32 v[2:3], v[2:3], v[142:143]
	v_rcp_f32_e32 v6, v5
	v_pk_add_f32 v[0:1], v[0:1], v[140:141]
	v_pk_add_f32 v[2:3], v[2:3], v[138:139]
	v_pk_add_f32 v[0:1], v[0:1], v[136:137]
	v_pk_add_f32 v[2:3], v[2:3], v[134:135]
	v_pk_add_f32 v[0:1], v[0:1], v[132:133]
	v_pk_add_f32 v[2:3], v[2:3], v[130:131]
	v_pk_add_f32 v[0:1], v[0:1], v[128:129]
	v_pk_add_f32 v[2:3], v[2:3], v[126:127]
	v_fma_f32 v7, -v5, v6, 1.0
	v_pk_add_f32 v[0:1], v[0:1], v[124:125]
	v_pk_add_f32 v[2:3], v[2:3], v[122:123]
	v_fmac_f32_e32 v6, v7, v6
	v_div_scale_f32 v7, vcc, 1.0, v4, 1.0
	v_pk_add_f32 v[0:1], v[0:1], v[120:121]
	v_pk_add_f32 v[2:3], v[2:3], v[118:119]
	v_mul_f32_e32 v8, v7, v6
	v_pk_add_f32 v[0:1], v[0:1], v[116:117]
	v_pk_add_f32 v[2:3], v[2:3], v[114:115]
	v_fma_f32 v9, -v5, v8, v7
	v_pk_add_f32 v[0:1], v[0:1], v[112:113]
	v_pk_add_f32 v[2:3], v[2:3], v[110:111]
	v_fmac_f32_e32 v8, v9, v6
	v_pk_add_f32 v[0:1], v[0:1], v[108:109]
	v_pk_add_f32 v[2:3], v[2:3], v[106:107]
	v_fma_f32 v5, -v5, v8, v7
	v_pk_add_f32 v[0:1], v[0:1], v[104:105]
	v_pk_add_f32 v[2:3], v[2:3], v[102:103]
	v_div_fmas_f32 v5, v5, v6, v8
	v_lshlrev_b32_e32 v92, 16, v94
	v_and_b32_e32 v93, 0xffff0000, v94
	v_lshlrev_b32_e32 v94, 16, v95
	v_and_b32_e32 v95, 0xffff0000, v95
	v_pk_add_f32 v[0:1], v[0:1], v[100:101]
	v_pk_add_f32 v[2:3], v[2:3], v[98:99]
	v_div_fixup_f32 v4, v5, v4, 1.0
	v_pk_add_f32 v[0:1], v[0:1], v[96:97]
	v_pk_add_f32 v[2:3], v[2:3], v[94:95]
	v_cndmask_b32_e64 v4, v4, v149, s[8:9]
	v_xor_b32_e32 v7, 0x80000000, v95
	v_xor_b32_e32 v6, 0x80000000, v94
	v_pk_add_f32 v[0:1], v[0:1], v[92:93]
	v_pk_fma_f32 v[2:3], v[4:5], v[2:3], v[6:7] op_sel_hi:[0,1,1]
	v_xor_b32_e32 v7, 0x80000000, v93
	v_xor_b32_e32 v6, 0x80000000, v92
	s_or_b32 s22, s27, 14
	v_pk_fma_f32 v[0:1], v[4:5], v[0:1], v[6:7] op_sel_hi:[0,1,1]
	s_min_u32 s22, s22, 15
	v_cvt_pk_bf16_f32 v0, v0, v1
	v_cvt_pk_bf16_f32 v1, v2, v3
	v_lshl_add_u64 v[2:3], v[70:71], 0, s[50:51]
	s_add_i32 s22, s22, 1
	global_store_dwordx2 v[2:3], v[0:1], off
	v_pk_add_f32 v[2:3], v[58:59], v[146:147]
	v_cvt_f32_ubyte0_e32 v4, s22
	v_pk_add_f32 v[0:1], v[56:57], v[144:145]
	v_pk_add_f32 v[2:3], v[2:3], v[142:143]
	v_div_scale_f32 v5, s[34:35], v4, v4, 1.0
	v_pk_add_f32 v[0:1], v[0:1], v[140:141]
	v_pk_add_f32 v[2:3], v[2:3], v[138:139]
; __device__ __forceinline__ unsigned pk2(float lo, float hi) { unsigned r; asm volatile("v_cvt_pk_bf16_f32 %0, %1, %2" : "=v"(r) : "v"(lo), "v"(hi)); return r; }
; __device__ __forceinline__ float bf_lo(unsigned w) { return __uint_as_float(w << 16); }
; __device__ __forceinline__ float bf_hi(unsigned w) { return __uint_as_float(w & 0xffff0000u); }
; template <int GI> __device__ __forceinline__ void p4_dpass(const bf16_t* XB, const float* cache, bf16_t* Dm, int strip, int lane) {
;     ...
;         if (i >= W - 1 || pos0 != 0) { const u32x2 w = *(const u32x2*)(XB + (size_t)(tok0 - (W - 1) + i) * 1024 + c); rows[i] = (f32x4){bf_lo(w.x), bf_hi(w.x), bf_lo(w.y), bf_hi(w.y)}; }
;         else if (samp) rows[i] = *(const f32x4*)(cache + ((size_t)b * 15 + 15 - (W - 1) + i) * 1024 + c);
;         else rows[i] = (f32x4){0.f, 0.f, 0.f, 0.f};
;     }
; #pragma unroll
;     for (int t = 0; t < 16; ++t) {
;         f32x4 s = rows[t];
; #pragma unroll
;         for (int j = 1; j < W; ++j) s += rows[t + j];
;         const int cnt = samp ? W : (W < pos0 + t + 1 ? W : pos0 + t + 1);
;         const f32x4 d = s * (1.0f / (float)cnt) - rows[t + W - 1];
;         u32x2 wv; wv.x = pk2(d[0], d[1]); wv.y = pk2(d[2], d[3]);
;         *(u32x2*)(Dm + (size_t)(tok0 + t) * 1024 + c) = wv;
	v_rcp_f32_e32 v6, v5
	v_pk_add_f32 v[0:1], v[0:1], v[136:137]
	v_pk_add_f32 v[2:3], v[2:3], v[134:135]
	v_pk_add_f32 v[0:1], v[0:1], v[132:133]
	v_pk_add_f32 v[2:3], v[2:3], v[130:131]
	v_pk_add_f32 v[0:1], v[0:1], v[128:129]
	v_pk_add_f32 v[2:3], v[2:3], v[126:127]
	v_pk_add_f32 v[0:1], v[0:1], v[124:125]
	v_pk_add_f32 v[2:3], v[2:3], v[122:123]
	v_fma_f32 v7, -v5, v6, 1.0
	v_pk_add_f32 v[0:1], v[0:1], v[120:121]
	v_pk_add_f32 v[2:3], v[2:3], v[118:119]
	v_fmac_f32_e32 v6, v7, v6
	v_div_scale_f32 v7, vcc, 1.0, v4, 1.0
	v_pk_add_f32 v[0:1], v[0:1], v[116:117]
	v_pk_add_f32 v[2:3], v[2:3], v[114:115]
	v_mul_f32_e32 v8, v7, v6
	v_pk_add_f32 v[0:1], v[0:1], v[112:113]
	v_pk_add_f32 v[2:3], v[2:3], v[110:111]
	v_fma_f32 v9, -v5, v8, v7
	v_pk_add_f32 v[0:1], v[0:1], v[108:109]
	v_pk_add_f32 v[2:3], v[2:3], v[106:107]
	v_fmac_f32_e32 v8, v9, v6
	v_pk_add_f32 v[0:1], v[0:1], v[104:105]
	v_pk_add_f32 v[2:3], v[2:3], v[102:103]
	v_fma_f32 v5, -v5, v8, v7
	v_pk_add_f32 v[0:1], v[0:1], v[100:101]
	v_pk_add_f32 v[2:3], v[2:3], v[98:99]
	v_div_fmas_f32 v5, v5, v6, v8
	v_lshlrev_b32_e32 v88, 16, v90
	v_and_b32_e32 v89, 0xffff0000, v90
	v_lshlrev_b32_e32 v90, 16, v91
	v_and_b32_e32 v91, 0xffff0000, v91
	v_pk_add_f32 v[0:1], v[0:1], v[96:97]
	v_pk_add_f32 v[2:3], v[2:3], v[94:95]
	v_div_fixup_f32 v4, v5, v4, 1.0
	v_pk_add_f32 v[0:1], v[0:1], v[92:93]
	v_pk_add_f32 v[2:3], v[2:3], v[90:91]
	v_cndmask_b32_e64 v4, v4, v149, s[8:9]
	v_xor_b32_e32 v7, 0x80000000, v91
	v_xor_b32_e32 v6, 0x80000000, v90
	v_pk_add_f32 v[0:1], v[0:1], v[88:89]
	v_pk_fma_f32 v[2:3], v[4:5], v[2:3], v[6:7] op_sel_hi:[0,1,1]
	v_xor_b32_e32 v7, 0x80000000, v89
	v_xor_b32_e32 v6, 0x80000000, v88
	v_pk_fma_f32 v[0:1], v[4:5], v[0:1], v[6:7] op_sel_hi:[0,1,1]
	v_cvt_pk_bf16_f32 v0, v0, v1
	v_cvt_pk_bf16_f32 v1, v2, v3
	v_lshl_add_u64 v[2:3], v[70:71], 0, s[48:49]
	global_store_dwordx2 v[2:3], v[0:1], off
	v_pk_add_f32 v[2:3], v[146:147], v[142:143]
	v_pk_add_f32 v[0:1], v[144:145], v[140:141]
	v_pk_add_f32 v[2:3], v[2:3], v[138:139]
	v_pk_add_f32 v[0:1], v[0:1], v[136:137]
	v_pk_add_f32 v[2:3], v[2:3], v[134:135]
	v_pk_add_f32 v[0:1], v[0:1], v[132:133]
	v_pk_add_f32 v[2:3], v[2:3], v[130:131]
	v_pk_add_f32 v[0:1], v[0:1], v[128:129]
	v_pk_add_f32 v[2:3], v[2:3], v[126:127]
	v_pk_add_f32 v[0:1], v[0:1], v[124:125]
	v_pk_add_f32 v[2:3], v[2:3], v[122:123]
	v_pk_add_f32 v[0:1], v[0:1], v[120:121]
	v_pk_add_f32 v[2:3], v[2:3], v[118:119]
	v_pk_add_f32 v[0:1], v[0:1], v[116:117]
	v_pk_add_f32 v[2:3], v[2:3], v[114:115]
	v_pk_add_f32 v[0:1], v[0:1], v[112:113]
	v_pk_add_f32 v[2:3], v[2:3], v[110:111]
	v_pk_add_f32 v[0:1], v[0:1], v[108:109]
	v_pk_add_f32 v[2:3], v[2:3], v[106:107]
	v_pk_add_f32 v[0:1], v[0:1], v[104:105]
	v_pk_add_f32 v[2:3], v[2:3], v[102:103]
	v_pk_add_f32 v[0:1], v[0:1], v[100:101]
	v_pk_add_f32 v[2:3], v[2:3], v[98:99]
	v_pk_add_f32 v[0:1], v[0:1], v[96:97]
	v_pk_add_f32 v[2:3], v[2:3], v[94:95]
	v_lshlrev_b32_e32 v84, 16, v86
	v_and_b32_e32 v85, 0xffff0000, v86
	v_lshlrev_b32_e32 v86, 16, v87
	v_and_b32_e32 v87, 0xffff0000, v87
	v_pk_add_f32 v[0:1], v[0:1], v[92:93]
	v_pk_add_f32 v[2:3], v[2:3], v[90:91]
	v_pk_add_f32 v[0:1], v[0:1], v[88:89]
	v_pk_add_f32 v[2:3], v[2:3], v[86:87]
	v_xor_b32_e32 v5, 0x80000000, v87
	v_xor_b32_e32 v4, 0x80000000, v86
	v_pk_add_f32 v[0:1], v[0:1], v[84:85]
	v_pk_fma_f32 v[2:3], v[2:3], s[36:37], v[4:5] op_sel_hi:[1,0,1]
	v_xor_b32_e32 v5, 0x80000000, v85
	v_xor_b32_e32 v4, 0x80000000, v84
	v_pk_fma_f32 v[0:1], v[0:1], s[36:37], v[4:5] op_sel_hi:[1,0,1]
	s_mov_b64 s[34:35], 0
	v_cvt_pk_bf16_f32 v0, v0, v1
	v_cvt_pk_bf16_f32 v1, v2, v3
	v_lshl_add_u64 v[2:3], v[70:71], 0, s[46:47]
	global_store_dwordx2 v[2:3], v[0:1], off
